# dn_chunk solve: 90 v_fmac x, -0.0, y no-ops (masked upper-triangle terms) removed
# speedup vs baseline: 1.0086x; 1.0007x over previous
.LBB0_1308:
	v_mov_b32_e32 v25, s16
	v_and_b32_e32 v24, 64, v86
	v_cmp_eq_u32_e64 s[2:3], 0, v24
	v_mov_b32_e32 v24, s17
	s_movk_i32 s4, 0x80
	v_cndmask_b32_e64 v24, v24, v25, s[2:3]
	v_lshlrev_b32_e32 v25, 1, v86
	v_cmp_gt_u32_e32 vcc, s4, v86
	v_and_b32_e32 v26, 0xffffff00, v25
	v_readlane_b32 s4, v253, 26
	v_add_u32_e32 v84, v24, v26
	v_mov_b32_e32 v26, s15
	v_mov_b32_e32 v24, s4
	v_cndmask_b32_e32 v92, v24, v26, vcc
	v_mov_b32_e32 v24, s33
	v_mov_b32_e32 v26, s14
	v_cndmask_b32_e64 v24, v24, v26, s[2:3]
	v_cndmask_b32_e64 v26, v196, 0, vcc
	v_and_b32_e32 v128, 0x7e, v25
	v_add3_u32 v40, v24, v26, v128
	v_cndmask_b32_e32 v97, v197, v198, vcc
	v_add_u32_e32 v44, v40, v97
	ds_read_b128 v[36:39], v84
	ds_read_b128 v[32:35], v84 offset:16
	ds_read_b128 v[28:31], v84 offset:32
	ds_read_b128 v[24:27], v84 offset:48
	ds_read_u16 v40, v40
	s_brev_b32 s4, 1
	s_waitcnt lgkmcnt(0)
	v_lshlrev_b32_e32 v40, 16, v40
	v_fma_f32 v89, v36, v40, 0
	v_add_u32_e32 v36, v44, v97
	ds_read_b128 v[40:43], v92 offset:256
	ds_read_u16 v44, v44
	s_waitcnt lgkmcnt(1)
	v_mul_f32_e32 v40, v40, v89
	s_waitcnt lgkmcnt(0)
	v_lshlrev_b32_e32 v44, 16, v44
	v_fma_f32 v43, v43, s4, 0
	v_fma_f32 v42, v42, s4, 0
	v_fma_f32 v41, v41, s4, 0
	v_fma_f32 v37, v37, v44, -v40
	v_add_f32_e32 v37, v41, v37
	v_add_f32_e32 v40, v42, v43
	v_add_f32_e32 v90, v40, v37
	v_add_u32_e32 v37, v36, v97
	ds_read_b128 v[40:43], v92 offset:512
	ds_read_u16 v36, v36
	v_add_u32_e32 v44, v37, v97
	ds_read_u16 v37, v37
	v_add_u32_e32 v45, v44, v97
	s_waitcnt lgkmcnt(2)
	v_mul_f32_e32 v40, v40, v89
	s_waitcnt lgkmcnt(1)
	v_lshlrev_b32_e32 v36, 16, v36
	v_fma_f32 v43, v43, s4, 0
	v_fma_f32 v42, v42, s4, 0
	v_fma_f32 v41, -v41, v90, 0
	v_fma_f32 v36, v38, v36, -v40
	v_add_f32_e32 v36, v36, v41
	v_add_f32_e32 v38, v42, v43
	ds_read_b128 v[40:43], v92 offset:768
	v_add_f32_e32 v91, v38, v36
	s_waitcnt lgkmcnt(1)
	v_lshlrev_b32_e32 v37, 16, v37
	s_waitcnt lgkmcnt(0)
	v_mul_f32_e32 v40, v89, v40
	v_fma_f32 v36, v43, s4, 0
	v_fma_f32 v38, -v42, v91, 0
	v_fma_f32 v41, -v41, v90, 0
	v_fma_f32 v37, v39, v37, -v40
	v_add_f32_e32 v37, v41, v37
	v_add_f32_e32 v36, v36, v38
	v_add_f32_e32 v93, v37, v36
	ds_read_b128 v[36:39], v92 offset:1024
	ds_read_u16 v40, v44
	s_waitcnt lgkmcnt(1)
	v_mul_f32_e32 v36, v89, v36
	s_waitcnt lgkmcnt(0)
	v_lshlrev_b32_e32 v40, 16, v40
	v_fma_f32 v39, -v39, v93, 0
	v_fma_f32 v38, -v38, v91, 0
	v_fma_f32 v37, -v90, v37, 0
	v_fma_f32 v32, v32, v40, -v36
	v_add_f32_e32 v32, v37, v32
	v_add_f32_e32 v36, v38, v39
	v_add_f32_e32 v94, v32, v36
	ds_read_b128 v[36:39], v92 offset:1280
	ds_read_b128 v[40:43], v92 offset:1296
	v_add_u32_e32 v32, v45, v97
	s_waitcnt lgkmcnt(1)
	v_fma_f32 v37, -v90, v37, 0
	s_waitcnt lgkmcnt(0)
	ds_read_u16 v41, v45
	v_mul_f32_e32 v36, v89, v36
	v_fma_f32 v39, -v39, v93, 0
	v_fma_f32 v38, -v38, v91, 0
	s_waitcnt lgkmcnt(0)
	v_lshlrev_b32_e32 v41, 16, v41
	v_fma_f32 v33, v33, v41, -v36
	v_fma_f32 v33, -v40, v94, v33
	v_add_f32_e32 v33, v37, v33
	v_add_f32_e32 v36, v38, v39
	v_add_f32_e32 v95, v36, v33
	v_add_u32_e32 v33, v32, v97
	ds_read_b128 v[36:39], v92 offset:1536
	ds_read_u16 v32, v32
	ds_read_b128 v[40:43], v92 offset:1552
	v_add_u32_e32 v44, v33, v97
	ds_read_u16 v33, v33
	s_waitcnt lgkmcnt(3)
	v_mul_f32_e32 v36, v89, v36
	s_waitcnt lgkmcnt(2)
	v_lshlrev_b32_e32 v32, 16, v32
	v_fma_f32 v39, -v39, v93, 0
	v_fma_f32 v38, -v91, v38, 0
	v_fma_f32 v37, -v90, v37, 0
	v_fma_f32 v32, v34, v32, -v36
	s_waitcnt lgkmcnt(1)
	v_fma_f32 v37, -v41, v95, v37
	v_fma_f32 v32, -v40, v94, v32
	v_add_f32_e32 v32, v32, v37
	v_add_f32_e32 v34, v38, v39
	ds_read_b128 v[36:39], v92 offset:1792
	ds_read_b128 v[40:43], v92 offset:1808
	s_waitcnt lgkmcnt(2)
	v_lshlrev_b32_e32 v33, 16, v33
	v_add_f32_e32 v96, v34, v32
	v_add_u32_e32 v45, v44, v97
	s_waitcnt lgkmcnt(1)
	v_mul_f32_e32 v36, v89, v36
	v_fma_f32 v32, -v93, v39, 0
	v_fma_f32 v34, -v91, v38, 0
	v_fma_f32 v37, -v90, v37, 0
	v_fma_f32 v33, v35, v33, -v36
	s_waitcnt lgkmcnt(0)
	v_fma_f32 v34, -v42, v96, v34
	v_fma_f32 v37, -v41, v95, v37
	v_fma_f32 v33, -v94, v40, v33
	v_add_f32_e32 v33, v37, v33
	v_add_f32_e32 v32, v32, v34
	v_add_f32_e32 v98, v33, v32
	ds_read_b128 v[32:35], v92 offset:2048
	ds_read_b128 v[36:39], v92 offset:2064
	ds_read_b128 v[40:43], v92 offset:2336
	s_waitcnt lgkmcnt(2)
	v_fma_f32 v33, -v90, v33, 0
	s_waitcnt lgkmcnt(1)
	v_fma_f32 v33, -v95, v37, v33
	ds_read_u16 v37, v44
	v_mul_f32_e32 v32, v89, v32
	v_fma_f32 v35, -v93, v35, 0
	v_fma_f32 v34, -v91, v34, 0
	v_fma_f32 v35, -v39, v98, v35
	s_waitcnt lgkmcnt(0)
	v_lshlrev_b32_e32 v37, 16, v37
	v_fma_f32 v28, v28, v37, -v32
	v_fma_f32 v34, -v38, v96, v34
	v_fma_f32 v28, -v94, v36, v28
	v_add_f32_e32 v28, v33, v28
	v_add_f32_e32 v32, v34, v35
	v_add_f32_e32 v99, v28, v32
	ds_read_b128 v[32:35], v92 offset:2304
	ds_read_b128 v[36:39], v92 offset:2320
	v_add_u32_e32 v28, v45, v97
	s_waitcnt lgkmcnt(1)
	v_fma_f32 v33, -v90, v33, 0
	s_waitcnt lgkmcnt(0)
	v_fma_f32 v33, -v95, v37, v33
	ds_read_u16 v37, v45
	v_mul_f32_e32 v32, v89, v32
	v_fma_f32 v35, -v93, v35, 0
	v_fma_f32 v34, -v91, v34, 0
	v_fma_f32 v35, -v39, v98, v35
	s_waitcnt lgkmcnt(0)
	v_lshlrev_b32_e32 v37, 16, v37
	v_fma_f32 v29, v29, v37, -v32
	v_fma_f32 v34, -v96, v38, v34
	v_fma_f32 v29, -v94, v36, v29
	v_fma_f32 v29, -v40, v99, v29
	v_add_f32_e32 v29, v33, v29
	v_add_f32_e32 v32, v34, v35
	v_add_f32_e32 v100, v32, v29
	v_add_u32_e32 v29, v28, v97
	ds_read_b128 v[32:35], v92 offset:2560
	ds_read_u16 v28, v28
	ds_read_b128 v[36:39], v92 offset:2576
	ds_read_b128 v[40:43], v92 offset:2592
	v_add_u32_e32 v44, v29, v97
	s_waitcnt lgkmcnt(3)
	v_mul_f32_e32 v32, v89, v32
	s_waitcnt lgkmcnt(2)
	v_lshlrev_b32_e32 v28, 16, v28
	v_fma_f32 v35, -v93, v35, 0
	v_fma_f32 v34, -v91, v34, 0
	v_fma_f32 v33, -v90, v33, 0
	v_fma_f32 v28, v30, v28, -v32
	s_waitcnt lgkmcnt(1)
	v_fma_f32 v35, -v98, v39, v35
	v_fma_f32 v34, -v96, v38, v34
	v_fma_f32 v33, -v95, v37, v33
	v_fma_f32 v28, -v94, v36, v28
	s_waitcnt lgkmcnt(0)
	v_fma_f32 v33, -v41, v100, v33
	v_fma_f32 v28, -v40, v99, v28
	v_add_f32_e32 v28, v33, v28
	v_add_f32_e32 v30, v34, v35
	ds_read_b128 v[32:35], v92 offset:2816
	ds_read_u16 v29, v29
	ds_read_b128 v[36:39], v92 offset:2832
	ds_read_b128 v[40:43], v92 offset:2848
	v_add_f32_e32 v101, v30, v28
	s_waitcnt lgkmcnt(3)
	v_mul_f32_e32 v32, v89, v32
	s_waitcnt lgkmcnt(2)
	v_lshlrev_b32_e32 v29, 16, v29
	v_fma_f32 v28, -v93, v35, 0
	v_fma_f32 v30, -v91, v34, 0
	v_fma_f32 v33, -v90, v33, 0
	v_fma_f32 v29, v31, v29, -v32
	s_waitcnt lgkmcnt(1)
	v_fma_f32 v28, -v98, v39, v28
	v_fma_f32 v30, -v96, v38, v30
	v_fma_f32 v33, -v95, v37, v33
	v_fma_f32 v29, -v94, v36, v29
	s_waitcnt lgkmcnt(0)
	v_fma_f32 v30, -v42, v101, v30
	v_fma_f32 v33, -v41, v100, v33
	v_fma_f32 v29, -v99, v40, v29
	v_add_f32_e32 v29, v33, v29
	v_add_f32_e32 v28, v28, v30
	v_add_f32_e32 v102, v28, v29
	ds_read_b128 v[28:31], v92 offset:3072
	ds_read_b128 v[32:35], v92 offset:3088
	ds_read_b128 v[36:39], v92 offset:3104
	v_add_u32_e32 v45, v44, v97
	ds_read_b128 v[40:43], v92 offset:3376
	s_waitcnt lgkmcnt(3)
	v_fma_f32 v29, -v90, v29, 0
	s_waitcnt lgkmcnt(2)
	v_fma_f32 v29, -v95, v33, v29
	ds_read_u16 v33, v44
	v_mul_f32_e32 v28, v89, v28
	v_fma_f32 v31, -v93, v31, 0
	v_fma_f32 v30, -v91, v30, 0
	v_fma_f32 v31, -v98, v35, v31
	s_waitcnt lgkmcnt(0)
	v_lshlrev_b32_e32 v33, 16, v33
	v_fma_f32 v24, v24, v33, -v28
	v_fma_f32 v30, -v96, v34, v30
	v_fma_f32 v24, -v94, v32, v24
	v_fma_f32 v31, -v39, v102, v31
	v_fma_f32 v30, -v38, v101, v30
	v_fma_f32 v29, -v100, v37, v29
	v_fma_f32 v24, -v99, v36, v24
	v_add_f32_e32 v24, v29, v24
	v_add_f32_e32 v28, v30, v31
	v_add_f32_e32 v103, v28, v24
	ds_read_b128 v[28:31], v92 offset:3328
	ds_read_b128 v[32:35], v92 offset:3344
	ds_read_b128 v[36:39], v92 offset:3360
	v_add_u32_e32 v24, v45, v97
	s_waitcnt lgkmcnt(2)
	v_fma_f32 v29, -v90, v29, 0
	s_waitcnt lgkmcnt(1)
	v_fma_f32 v29, -v95, v33, v29
	ds_read_u16 v33, v45
	v_mul_f32_e32 v28, v89, v28
	v_fma_f32 v31, -v93, v31, 0
	v_fma_f32 v30, -v91, v30, 0
	v_fma_f32 v31, -v98, v35, v31
	s_waitcnt lgkmcnt(0)
	v_lshlrev_b32_e32 v33, 16, v33
	v_fma_f32 v25, v25, v33, -v28
	v_fma_f32 v30, -v96, v34, v30
	v_fma_f32 v25, -v94, v32, v25
	v_fma_f32 v31, -v39, v102, v31
	v_fma_f32 v30, -v101, v38, v30
	v_fma_f32 v29, -v100, v37, v29
	v_fma_f32 v25, -v99, v36, v25
	v_fma_f32 v25, -v40, v103, v25
	v_add_f32_e32 v25, v29, v25
	v_add_f32_e32 v28, v30, v31
	v_add_f32_e32 v104, v28, v25
	v_add_u32_e32 v25, v24, v97
	ds_read_b128 v[28:31], v92 offset:3584
	ds_read_u16 v24, v24
	ds_read_b128 v[32:35], v92 offset:3600
	ds_read_b128 v[36:39], v92 offset:3616
	ds_read_b128 v[40:43], v92 offset:3632
	s_waitcnt lgkmcnt(4)
	v_mul_f32_e32 v28, v89, v28
	s_waitcnt lgkmcnt(3)
	v_lshlrev_b32_e32 v24, 16, v24
	v_fma_f32 v31, -v93, v31, 0
	v_fma_f32 v30, -v91, v30, 0
	v_fma_f32 v29, -v90, v29, 0
	v_fma_f32 v24, v26, v24, -v28
	s_waitcnt lgkmcnt(2)
	v_fma_f32 v31, -v98, v35, v31
	v_fma_f32 v30, -v96, v34, v30
	v_fma_f32 v29, -v95, v33, v29
	v_fma_f32 v24, -v94, v32, v24
	s_waitcnt lgkmcnt(1)
	v_fma_f32 v31, -v102, v39, v31
	v_fma_f32 v30, -v101, v38, v30
	v_fma_f32 v29, -v100, v37, v29
	v_fma_f32 v24, -v99, v36, v24
	s_waitcnt lgkmcnt(0)
	v_fma_f32 v29, -v41, v104, v29
	v_fma_f32 v24, -v103, v40, v24
	v_add_f32_e32 v24, v29, v24
	v_add_f32_e32 v26, v30, v31
	v_add_u32_e32 v44, v25, v97
	ds_read_b128 v[28:31], v92 offset:3840
	ds_read_u16 v25, v25
	ds_read_b128 v[32:35], v92 offset:3856
	ds_read_b128 v[36:39], v92 offset:3872
	ds_read_b128 v[40:43], v92 offset:3888
	s_waitcnt lgkmcnt(4)
	v_mul_f32_e32 v28, v89, v28
	s_waitcnt lgkmcnt(3)
	v_lshlrev_b32_e32 v25, 16, v25
	v_add_f32_e32 v105, v26, v24
	v_fma_f32 v24, -v93, v31, 0
	v_fma_f32 v26, -v91, v30, 0
	v_fma_f32 v29, -v90, v29, 0
	v_fma_f32 v25, v27, v25, -v28
	s_waitcnt lgkmcnt(2)
	v_fma_f32 v24, -v98, v35, v24
	v_fma_f32 v26, -v96, v34, v26
	v_fma_f32 v29, -v95, v33, v29
	v_fma_f32 v25, -v94, v32, v25
	s_waitcnt lgkmcnt(1)
	v_fma_f32 v24, -v102, v39, v24
	v_fma_f32 v26, -v101, v38, v26
	v_fma_f32 v29, -v100, v37, v29
	v_fma_f32 v25, -v99, v36, v25
	s_waitcnt lgkmcnt(0)
	v_fma_f32 v26, -v42, v105, v26
	v_fma_f32 v29, -v104, v41, v29
	v_fma_f32 v25, -v103, v40, v25
	v_add_f32_e32 v25, v29, v25
	v_add_f32_e32 v24, v24, v26
	v_add_f32_e32 v106, v24, v25
	ds_read_b128 v[24:27], v92 offset:4096
	ds_read_b128 v[28:31], v92 offset:4112
	ds_read_b128 v[32:35], v92 offset:4128
	ds_read_b128 v[36:39], v92 offset:4144
	v_add_u32_e32 v50, v44, v97
	s_waitcnt lgkmcnt(3)
	v_fma_f32 v27, -v93, v27, 0
	v_fma_f32 v26, -v91, v26, 0
	s_waitcnt lgkmcnt(2)
	v_fma_f32 v27, -v98, v31, v27
	v_fma_f32 v26, -v96, v30, v26
	s_waitcnt lgkmcnt(1)
	v_fma_f32 v27, -v102, v35, v27
	v_fma_f32 v26, -v101, v34, v26
	v_fma_f32 v25, -v90, v25, 0
	s_waitcnt lgkmcnt(0)
	v_fma_f32 v27, -v39, v106, v27
	v_fma_f32 v26, -v105, v38, v26
	v_fma_f32 v25, -v95, v29, v25
	ds_read_b128 v[38:41], v84 offset:64
	ds_read_u16 v29, v44
	v_mul_f32_e32 v24, v89, v24
	v_fma_f32 v25, -v100, v33, v25
	v_fma_f32 v25, -v104, v37, v25
	ds_read_b128 v[42:45], v92 offset:4400
	ds_read_b128 v[46:49], v92 offset:4416
	s_waitcnt lgkmcnt(2)
	v_lshlrev_b32_e32 v29, 16, v29
	v_fma_f32 v24, v38, v29, -v24
	v_fma_f32 v24, -v94, v28, v24
	v_fma_f32 v24, -v99, v32, v24
	v_fma_f32 v24, -v103, v36, v24
	v_add_f32_e32 v24, v25, v24
	v_add_f32_e32 v25, v26, v27
	v_add_f32_e32 v107, v25, v24
	ds_read_b128 v[24:27], v92 offset:4352
	ds_read_b128 v[28:31], v92 offset:4368
	ds_read_b128 v[32:35], v92 offset:4384
	v_add_u32_e32 v51, v50, v97
	s_waitcnt lgkmcnt(2)
	v_fma_f32 v25, -v90, v25, 0
	s_waitcnt lgkmcnt(1)
	v_fma_f32 v25, -v95, v29, v25
	ds_read_u16 v29, v50
	v_mul_f32_e32 v24, v89, v24
	v_fma_f32 v27, -v93, v27, 0
	v_fma_f32 v26, -v91, v26, 0
	v_fma_f32 v27, -v98, v31, v27
	s_waitcnt lgkmcnt(0)
	v_lshlrev_b32_e32 v29, 16, v29
	v_fma_f32 v24, v39, v29, -v24
	v_fma_f32 v26, -v96, v30, v26
	v_fma_f32 v24, -v94, v28, v24
	v_fma_f32 v27, -v102, v35, v27
	v_fma_f32 v26, -v101, v34, v26
	v_fma_f32 v25, -v100, v33, v25
	v_fma_f32 v24, -v99, v32, v24
	v_fma_f32 v27, -v106, v45, v27
	v_fma_f32 v26, -v105, v44, v26
	v_fma_f32 v25, -v104, v43, v25
	v_fma_f32 v24, -v103, v42, v24
	v_fma_f32 v24, -v46, v107, v24
	v_add_f32_e32 v24, v25, v24
	v_add_f32_e32 v25, v26, v27
	v_add_f32_e32 v108, v25, v24
	ds_read_b128 v[24:27], v92 offset:4608
	ds_read_b128 v[28:31], v92 offset:4624
	ds_read_b128 v[32:35], v92 offset:4640
	ds_read_b128 v[36:39], v92 offset:4656
	ds_read_b128 v[42:45], v92 offset:4672
	s_waitcnt lgkmcnt(4)
	v_fma_f32 v25, -v90, v25, 0
	s_waitcnt lgkmcnt(3)
	v_fma_f32 v25, -v95, v29, v25
	ds_read_u16 v29, v51
	v_mul_f32_e32 v24, v89, v24
	v_fma_f32 v27, -v93, v27, 0
	v_fma_f32 v26, -v91, v26, 0
	v_fma_f32 v27, -v98, v31, v27
	s_waitcnt lgkmcnt(0)
	v_lshlrev_b32_e32 v29, 16, v29
	v_fma_f32 v24, v40, v29, -v24
	v_fma_f32 v26, -v96, v30, v26
	v_fma_f32 v24, -v94, v28, v24
	v_fma_f32 v27, -v102, v35, v27
	v_fma_f32 v26, -v101, v34, v26
	v_fma_f32 v25, -v100, v33, v25
	v_fma_f32 v24, -v99, v32, v24
	v_fma_f32 v27, -v106, v39, v27
	v_fma_f32 v26, -v105, v38, v26
	v_fma_f32 v25, -v104, v37, v25
	v_fma_f32 v24, -v103, v36, v24
	v_fma_f32 v25, -v43, v108, v25
	v_fma_f32 v24, -v107, v42, v24
	v_add_f32_e32 v24, v25, v24
	v_add_f32_e32 v25, v26, v27
	v_add_f32_e32 v109, v25, v24
	ds_read_b128 v[24:27], v92 offset:4864
	ds_read_b128 v[28:31], v92 offset:4880
	v_add_u32_e32 v46, v51, v97
	ds_read_b128 v[32:35], v92 offset:4896
	ds_read_b128 v[36:39], v92 offset:4912
	s_waitcnt lgkmcnt(3)
	v_fma_f32 v25, -v90, v25, 0
	s_waitcnt lgkmcnt(2)
	v_fma_f32 v25, -v95, v29, v25
	ds_read_u16 v29, v46
	ds_read_b128 v[42:45], v92 offset:4928
	v_mul_f32_e32 v24, v89, v24
	v_fma_f32 v27, -v93, v27, 0
	v_fma_f32 v26, -v91, v26, 0
	s_waitcnt lgkmcnt(1)
	v_lshlrev_b32_e32 v29, 16, v29
	v_fma_f32 v24, v41, v29, -v24
	v_fma_f32 v27, -v98, v31, v27
	v_fma_f32 v26, -v96, v30, v26
	v_fma_f32 v24, -v94, v28, v24
	ds_read_b128 v[28:31], v92 offset:5120
	v_fma_f32 v27, -v102, v35, v27
	v_fma_f32 v26, -v101, v34, v26
	v_fma_f32 v25, -v100, v33, v25
	v_fma_f32 v24, -v99, v32, v24
	ds_read_b128 v[32:35], v92 offset:5136
	v_fma_f32 v27, -v106, v39, v27
	v_fma_f32 v26, -v105, v38, v26
	v_fma_f32 v25, -v104, v37, v25
	v_fma_f32 v24, -v103, v36, v24
	ds_read_b128 v[36:39], v92 offset:5152
	s_waitcnt lgkmcnt(3)
	v_fma_f32 v26, -v44, v109, v26
	v_fma_f32 v25, -v108, v43, v25
	v_fma_f32 v24, -v107, v42, v24
	ds_read_b128 v[40:43], v92 offset:5168
	v_add_u32_e32 v49, v46, v97
	v_add_f32_e32 v24, v25, v24
	v_add_f32_e32 v25, v27, v26
	ds_read_b128 v[44:47], v92 offset:5184
	v_add_f32_e32 v110, v25, v24
	s_waitcnt lgkmcnt(4)
	v_fma_f32 v24, -v93, v31, 0
	s_waitcnt lgkmcnt(3)
	v_fma_f32 v24, -v98, v35, v24
	s_waitcnt lgkmcnt(2)
	v_fma_f32 v24, -v102, v39, v24
	s_waitcnt lgkmcnt(1)
	v_fma_f32 v24, -v106, v43, v24
	s_waitcnt lgkmcnt(0)
	v_fma_f32 v31, -v47, v110, v24
	v_fma_f32 v24, -v91, v30, 0
	v_fma_f32 v24, -v96, v34, v24
	v_fma_f32 v24, -v101, v38, v24
	v_fma_f32 v24, -v105, v42, v24
	v_fma_f32 v30, -v109, v46, v24
	v_fma_f32 v24, -v90, v29, 0
	v_fma_f32 v24, -v95, v33, v24
	v_fma_f32 v24, -v100, v37, v24
	v_fma_f32 v24, -v104, v41, v24
	v_fma_f32 v29, -v108, v45, v24
	ds_read_b128 v[24:27], v84 offset:80
	ds_read_u16 v33, v49
	v_mul_f32_e32 v28, v89, v28
	v_add_u32_e32 v48, v49, v97
	ds_read_b128 v[50:53], v92 offset:5456
	s_waitcnt lgkmcnt(1)
	v_lshlrev_b32_e32 v33, 16, v33
	v_fma_f32 v24, v24, v33, -v28
	v_fma_f32 v24, -v94, v32, v24
	v_fma_f32 v24, -v99, v36, v24
	v_fma_f32 v24, -v103, v40, v24
	v_fma_f32 v24, -v107, v44, v24
	v_add_f32_e32 v24, v29, v24
	v_add_f32_e32 v28, v30, v31
	v_add_f32_e32 v111, v28, v24
	ds_read_b128 v[28:31], v92 offset:5376
	ds_read_b128 v[32:35], v92 offset:5392
	ds_read_b128 v[36:39], v92 offset:5408
	ds_read_b128 v[40:43], v92 offset:5424
	ds_read_b128 v[44:47], v92 offset:5440
	s_waitcnt lgkmcnt(4)
	v_fma_f32 v29, -v90, v29, 0
	s_waitcnt lgkmcnt(3)
	v_fma_f32 v29, -v95, v33, v29
	ds_read_u16 v33, v48
	v_mul_f32_e32 v28, v89, v28
	v_fma_f32 v31, -v93, v31, 0
	v_fma_f32 v30, -v91, v30, 0
	v_fma_f32 v31, -v98, v35, v31
	s_waitcnt lgkmcnt(0)
	v_lshlrev_b32_e32 v33, 16, v33
	v_fma_f32 v25, v25, v33, -v28
	v_fma_f32 v30, -v96, v34, v30
	v_fma_f32 v25, -v94, v32, v25
	v_fma_f32 v31, -v102, v39, v31
	v_fma_f32 v30, -v101, v38, v30
	v_fma_f32 v29, -v100, v37, v29
	v_fma_f32 v25, -v99, v36, v25
	v_fma_f32 v31, -v106, v43, v31
	v_fma_f32 v30, -v105, v42, v30
	v_fma_f32 v29, -v104, v41, v29
	v_fma_f32 v25, -v103, v40, v25
	v_fma_f32 v31, -v110, v47, v31
	v_fma_f32 v30, -v109, v46, v30
	v_fma_f32 v29, -v108, v45, v29
	v_fma_f32 v25, -v107, v44, v25
	v_fma_f32 v25, -v50, v111, v25
	v_add_u32_e32 v24, v48, v97
	v_add_f32_e32 v25, v29, v25
	v_add_f32_e32 v28, v30, v31
	v_add_f32_e32 v112, v28, v25
	v_add_u32_e32 v25, v24, v97
	ds_read_b128 v[28:31], v92 offset:5632
	ds_read_u16 v24, v24
	ds_read_b128 v[32:35], v92 offset:5648
	ds_read_b128 v[36:39], v92 offset:5664
	ds_read_b128 v[40:43], v92 offset:5680
	ds_read_b128 v[44:47], v92 offset:5696
	s_waitcnt lgkmcnt(4)
	v_lshlrev_b32_e32 v24, 16, v24
	v_mul_f32_e32 v28, v89, v28
	v_fma_f32 v31, -v93, v31, 0
	ds_read_b128 v[48:51], v92 offset:5712
	v_fma_f32 v30, -v91, v30, 0
	v_fma_f32 v29, -v90, v29, 0
	v_fma_f32 v24, v26, v24, -v28
	s_waitcnt lgkmcnt(4)
	v_fma_f32 v31, -v98, v35, v31
	v_fma_f32 v30, -v96, v34, v30
	v_fma_f32 v29, -v95, v33, v29
	v_fma_f32 v24, -v94, v32, v24
	s_waitcnt lgkmcnt(3)
	v_fma_f32 v31, -v102, v39, v31
	v_fma_f32 v30, -v101, v38, v30
	v_fma_f32 v29, -v100, v37, v29
	v_fma_f32 v24, -v99, v36, v24
	s_waitcnt lgkmcnt(2)
	v_fma_f32 v31, -v106, v43, v31
	v_fma_f32 v30, -v105, v42, v30
	v_fma_f32 v29, -v104, v41, v29
	v_fma_f32 v24, -v103, v40, v24
	s_waitcnt lgkmcnt(1)
	v_fma_f32 v31, -v110, v47, v31
	v_fma_f32 v30, -v109, v46, v30
	v_fma_f32 v29, -v108, v45, v29
	v_fma_f32 v24, -v107, v44, v24
	s_waitcnt lgkmcnt(0)
	v_fma_f32 v29, -v49, v112, v29
	v_fma_f32 v24, -v111, v48, v24
	v_add_f32_e32 v24, v29, v24
	v_add_f32_e32 v26, v30, v31
	v_add_u32_e32 v52, v25, v97
	ds_read_b128 v[28:31], v92 offset:5888
	ds_read_u16 v25, v25
	ds_read_b128 v[32:35], v92 offset:5904
	ds_read_b128 v[36:39], v92 offset:5920
	ds_read_b128 v[40:43], v92 offset:5936
	ds_read_b128 v[44:47], v92 offset:5952
	s_waitcnt lgkmcnt(4)
	v_lshlrev_b32_e32 v25, 16, v25
	v_mul_f32_e32 v28, v89, v28
	v_add_f32_e32 v113, v26, v24
	v_fma_f32 v24, -v93, v31, 0
	ds_read_b128 v[48:51], v92 offset:5968
	v_fma_f32 v26, -v91, v30, 0
	v_fma_f32 v29, -v90, v29, 0
	v_fma_f32 v25, v27, v25, -v28
	s_waitcnt lgkmcnt(4)
	v_fma_f32 v24, -v98, v35, v24
	v_fma_f32 v26, -v96, v34, v26
	v_fma_f32 v29, -v95, v33, v29
	v_fma_f32 v25, -v94, v32, v25
	s_waitcnt lgkmcnt(3)
	v_fma_f32 v24, -v102, v39, v24
	v_fma_f32 v26, -v101, v38, v26
	v_fma_f32 v29, -v100, v37, v29
	v_fma_f32 v25, -v99, v36, v25
	s_waitcnt lgkmcnt(2)
	v_fma_f32 v24, -v106, v43, v24
	v_fma_f32 v26, -v105, v42, v26
	v_fma_f32 v29, -v104, v41, v29
	v_fma_f32 v25, -v103, v40, v25
	s_waitcnt lgkmcnt(1)
	v_fma_f32 v24, -v110, v47, v24
	v_fma_f32 v26, -v109, v46, v26
	v_fma_f32 v29, -v108, v45, v29
	v_fma_f32 v25, -v107, v44, v25
	s_waitcnt lgkmcnt(0)
	v_fma_f32 v26, -v50, v113, v26
	v_fma_f32 v29, -v112, v49, v29
	v_fma_f32 v25, -v111, v48, v25
	v_add_f32_e32 v25, v29, v25
	v_add_f32_e32 v24, v24, v26
	v_add_f32_e32 v114, v24, v25
	ds_read_b128 v[24:27], v92 offset:6144
	ds_read_b128 v[28:31], v92 offset:6160
	ds_read_b128 v[32:35], v92 offset:6176
	ds_read_b128 v[36:39], v92 offset:6192
	ds_read_b128 v[40:43], v92 offset:6208
	s_waitcnt lgkmcnt(4)
	v_fma_f32 v27, -v93, v27, 0
	ds_read_b128 v[44:47], v92 offset:6224
	v_fma_f32 v26, -v91, v26, 0
	s_waitcnt lgkmcnt(4)
	v_fma_f32 v27, -v98, v31, v27
	v_fma_f32 v26, -v96, v30, v26
	s_waitcnt lgkmcnt(3)
	v_fma_f32 v27, -v102, v35, v27
	v_fma_f32 v26, -v101, v34, v26
	s_waitcnt lgkmcnt(2)
	v_fma_f32 v27, -v106, v39, v27
	v_fma_f32 v26, -v105, v38, v26
	s_waitcnt lgkmcnt(1)
	v_fma_f32 v27, -v110, v43, v27
	v_fma_f32 v26, -v109, v42, v26
	v_fma_f32 v25, -v90, v25, 0
	s_waitcnt lgkmcnt(0)
	v_fma_f32 v27, -v47, v114, v27
	v_fma_f32 v26, -v113, v46, v26
	v_fma_f32 v25, -v95, v29, v25
	ds_read_b128 v[46:49], v84 offset:96
	ds_read_u16 v29, v52
	v_mul_f32_e32 v24, v89, v24
	v_fma_f32 v25, -v100, v33, v25
	v_fma_f32 v25, -v104, v37, v25
	v_fma_f32 v25, -v108, v41, v25
	s_waitcnt lgkmcnt(0)
	v_lshlrev_b32_e32 v29, 16, v29
	v_fma_f32 v24, v46, v29, -v24
	v_fma_f32 v24, -v94, v28, v24
	v_fma_f32 v24, -v99, v32, v24
	v_fma_f32 v24, -v103, v36, v24
	v_fma_f32 v24, -v107, v40, v24
	v_fma_f32 v25, -v112, v45, v25
	v_fma_f32 v24, -v111, v44, v24
	v_add_f32_e32 v24, v25, v24
	v_add_f32_e32 v25, v26, v27
	v_add_f32_e32 v115, v25, v24
	ds_read_b128 v[24:27], v92 offset:6400
	ds_read_b128 v[28:31], v92 offset:6416
	v_add_u32_e32 v58, v52, v97
	ds_read_b128 v[32:35], v92 offset:6432
	ds_read_b128 v[36:39], v92 offset:6448
	s_waitcnt lgkmcnt(3)
	v_fma_f32 v25, -v90, v25, 0
	s_waitcnt lgkmcnt(2)
	v_fma_f32 v25, -v95, v29, v25
	ds_read_u16 v29, v58
	ds_read_b128 v[40:43], v92 offset:6464
	v_mul_f32_e32 v24, v89, v24
	v_fma_f32 v27, -v93, v27, 0
	ds_read_b128 v[50:53], v92 offset:6480
	ds_read_b128 v[54:57], v92 offset:6496
	s_waitcnt lgkmcnt(3)
	v_lshlrev_b32_e32 v29, 16, v29
	v_fma_f32 v26, -v91, v26, 0
	v_fma_f32 v24, v47, v29, -v24
	v_fma_f32 v27, -v98, v31, v27
	v_fma_f32 v26, -v96, v30, v26
	v_fma_f32 v24, -v94, v28, v24
	v_fma_f32 v27, -v102, v35, v27
	v_fma_f32 v26, -v101, v34, v26
	v_fma_f32 v25, -v100, v33, v25
	v_fma_f32 v24, -v99, v32, v24
	v_fma_f32 v27, -v106, v39, v27
	v_fma_f32 v26, -v105, v38, v26
	v_fma_f32 v25, -v104, v37, v25
	v_fma_f32 v24, -v103, v36, v24
	s_waitcnt lgkmcnt(2)
	v_fma_f32 v27, -v110, v43, v27
	v_fma_f32 v26, -v109, v42, v26
	v_fma_f32 v25, -v108, v41, v25
	v_fma_f32 v24, -v107, v40, v24
	s_waitcnt lgkmcnt(1)
	v_fma_f32 v27, -v114, v53, v27
	v_fma_f32 v26, -v113, v52, v26
	v_fma_f32 v25, -v112, v51, v25
	v_fma_f32 v24, -v111, v50, v24
	s_waitcnt lgkmcnt(0)
	v_fma_f32 v24, -v54, v115, v24
	v_add_f32_e32 v24, v25, v24
	v_add_f32_e32 v25, v26, v27
	v_add_f32_e32 v116, v25, v24
	ds_read_b128 v[24:27], v92 offset:6656
	ds_read_b128 v[28:31], v92 offset:6672
	v_add_u32_e32 v59, v58, v97
	ds_read_b128 v[32:35], v92 offset:6688
	ds_read_b128 v[36:39], v92 offset:6704
	s_waitcnt lgkmcnt(3)
	v_fma_f32 v25, -v90, v25, 0
	s_waitcnt lgkmcnt(2)
	v_fma_f32 v25, -v95, v29, v25
	ds_read_u16 v29, v59
	ds_read_b128 v[40:43], v92 offset:6720
	v_mul_f32_e32 v24, v89, v24
	v_fma_f32 v27, -v93, v27, 0
	ds_read_b128 v[44:47], v92 offset:6736
	s_waitcnt lgkmcnt(2)
	v_lshlrev_b32_e32 v29, 16, v29
	v_fma_f32 v26, -v91, v26, 0
	v_fma_f32 v24, v48, v29, -v24
	v_fma_f32 v27, -v98, v31, v27
	ds_read_b128 v[50:53], v92 offset:6752
	v_fma_f32 v26, -v96, v30, v26
	v_fma_f32 v24, -v94, v28, v24
	v_fma_f32 v27, -v102, v35, v27
	v_fma_f32 v26, -v101, v34, v26
	v_fma_f32 v25, -v100, v33, v25
	v_fma_f32 v24, -v99, v32, v24
	v_fma_f32 v27, -v106, v39, v27
	v_fma_f32 v26, -v105, v38, v26
	v_fma_f32 v25, -v104, v37, v25
	v_fma_f32 v24, -v103, v36, v24
	s_waitcnt lgkmcnt(2)
	v_fma_f32 v27, -v110, v43, v27
	v_fma_f32 v26, -v109, v42, v26
	v_fma_f32 v25, -v108, v41, v25
	v_fma_f32 v24, -v107, v40, v24
	s_waitcnt lgkmcnt(1)
	v_fma_f32 v27, -v114, v47, v27
	v_fma_f32 v26, -v113, v46, v26
	v_fma_f32 v25, -v112, v45, v25
	v_fma_f32 v24, -v111, v44, v24
	s_waitcnt lgkmcnt(0)
	v_fma_f32 v25, -v51, v116, v25
	v_fma_f32 v24, -v115, v50, v24
	v_add_f32_e32 v24, v25, v24
	v_add_f32_e32 v25, v26, v27
	v_add_f32_e32 v117, v25, v24
	ds_read_b128 v[24:27], v92 offset:6912
	ds_read_b128 v[28:31], v92 offset:6928
	v_add_u32_e32 v54, v59, v97
	ds_read_b128 v[32:35], v92 offset:6944
	ds_read_b128 v[36:39], v92 offset:6960
	s_waitcnt lgkmcnt(3)
	v_fma_f32 v25, -v90, v25, 0
	s_waitcnt lgkmcnt(2)
	v_fma_f32 v25, -v95, v29, v25
	ds_read_u16 v29, v54
	ds_read_b128 v[40:43], v92 offset:6976
	v_mul_f32_e32 v24, v89, v24
	v_fma_f32 v27, -v93, v27, 0
	ds_read_b128 v[44:47], v92 offset:6992
	s_waitcnt lgkmcnt(2)
	v_lshlrev_b32_e32 v29, 16, v29
	v_fma_f32 v26, -v91, v26, 0
	v_fma_f32 v24, v49, v29, -v24
	v_fma_f32 v27, -v98, v31, v27
	ds_read_b128 v[50:53], v92 offset:7008
	v_fma_f32 v26, -v96, v30, v26
	v_fma_f32 v24, -v94, v28, v24
	v_fma_f32 v27, -v102, v35, v27
	v_fma_f32 v26, -v101, v34, v26
	v_fma_f32 v25, -v100, v33, v25
	v_fma_f32 v24, -v99, v32, v24
	v_fma_f32 v27, -v106, v39, v27
	v_fma_f32 v26, -v105, v38, v26
	v_fma_f32 v25, -v104, v37, v25
	v_fma_f32 v24, -v103, v36, v24
	ds_read_b128 v[28:31], v92 offset:7168
	s_waitcnt lgkmcnt(3)
	v_fma_f32 v27, -v110, v43, v27
	v_fma_f32 v26, -v109, v42, v26
	v_fma_f32 v25, -v108, v41, v25
	v_fma_f32 v24, -v107, v40, v24
	ds_read_b128 v[32:35], v92 offset:7184
	s_waitcnt lgkmcnt(3)
	v_fma_f32 v27, -v114, v47, v27
	v_fma_f32 v26, -v113, v46, v26
	v_fma_f32 v25, -v112, v45, v25
	v_fma_f32 v24, -v111, v44, v24
	ds_read_b128 v[36:39], v92 offset:7200
	s_waitcnt lgkmcnt(3)
	v_fma_f32 v26, -v52, v117, v26
	v_fma_f32 v25, -v116, v51, v25
	v_fma_f32 v24, -v115, v50, v24
	ds_read_b128 v[40:43], v92 offset:7216
	v_add_f32_e32 v24, v25, v24
	v_add_f32_e32 v25, v27, v26
	ds_read_b128 v[44:47], v92 offset:7232
	v_add_f32_e32 v118, v25, v24
	s_waitcnt lgkmcnt(4)
	v_fma_f32 v24, -v93, v31, 0
	ds_read_b128 v[48:51], v92 offset:7248
	v_add_u32_e32 v57, v54, v97
	s_waitcnt lgkmcnt(4)
	v_fma_f32 v24, -v98, v35, v24
	ds_read_b128 v[52:55], v92 offset:7264
	s_waitcnt lgkmcnt(4)
	v_fma_f32 v24, -v102, v39, v24
	s_waitcnt lgkmcnt(3)
	v_fma_f32 v24, -v106, v43, v24
	s_waitcnt lgkmcnt(2)
	v_fma_f32 v24, -v110, v47, v24
	s_waitcnt lgkmcnt(1)
	v_fma_f32 v24, -v114, v51, v24
	s_waitcnt lgkmcnt(0)
	v_fma_f32 v31, -v55, v118, v24
	v_fma_f32 v24, -v91, v30, 0
	v_fma_f32 v24, -v96, v34, v24
	v_fma_f32 v24, -v101, v38, v24
	v_fma_f32 v24, -v105, v42, v24
	v_fma_f32 v24, -v109, v46, v24
	v_fma_f32 v24, -v113, v50, v24
	v_fma_f32 v30, -v117, v54, v24
	v_fma_f32 v24, -v90, v29, 0
	v_fma_f32 v24, -v95, v33, v24
	v_fma_f32 v24, -v100, v37, v24
	v_fma_f32 v24, -v104, v41, v24
	v_fma_f32 v24, -v108, v45, v24
	v_fma_f32 v24, -v112, v49, v24
	v_fma_f32 v29, -v116, v53, v24
	ds_read_b128 v[24:27], v84 offset:112
	ds_read_u16 v33, v57
	v_mul_f32_e32 v28, v89, v28
	v_add_u32_e32 v56, v57, v97
	ds_read_b128 v[58:61], v92 offset:7536
	s_waitcnt lgkmcnt(1)
	v_lshlrev_b32_e32 v33, 16, v33
	v_fma_f32 v24, v24, v33, -v28
	v_fma_f32 v24, -v94, v32, v24
	v_fma_f32 v24, -v99, v36, v24
	v_fma_f32 v24, -v103, v40, v24
	v_fma_f32 v24, -v107, v44, v24
	v_fma_f32 v24, -v111, v48, v24
	v_fma_f32 v24, -v115, v52, v24
	v_add_f32_e32 v24, v29, v24
	v_add_f32_e32 v28, v30, v31
	v_add_f32_e32 v119, v28, v24
	ds_read_b128 v[28:31], v92 offset:7424
	ds_read_b128 v[32:35], v92 offset:7440
	ds_read_b128 v[36:39], v92 offset:7456
	ds_read_b128 v[40:43], v92 offset:7472
	ds_read_b128 v[44:47], v92 offset:7488
	s_waitcnt lgkmcnt(4)
	v_fma_f32 v29, -v90, v29, 0
	s_waitcnt lgkmcnt(3)
	v_fma_f32 v29, -v95, v33, v29
	ds_read_u16 v33, v56
	v_mul_f32_e32 v28, v89, v28
	v_fma_f32 v31, -v93, v31, 0
	ds_read_b128 v[48:51], v92 offset:7504
	v_fma_f32 v30, -v91, v30, 0
	s_waitcnt lgkmcnt(1)
	v_lshlrev_b32_e32 v33, 16, v33
	v_fma_f32 v25, v25, v33, -v28
	v_fma_f32 v31, -v98, v35, v31
	ds_read_b128 v[52:55], v92 offset:7520
	v_fma_f32 v30, -v96, v34, v30
	v_fma_f32 v25, -v94, v32, v25
	v_fma_f32 v31, -v102, v39, v31
	v_fma_f32 v30, -v101, v38, v30
	v_fma_f32 v29, -v100, v37, v29
	v_fma_f32 v25, -v99, v36, v25
	v_fma_f32 v31, -v106, v43, v31
	v_fma_f32 v30, -v105, v42, v30
	v_fma_f32 v29, -v104, v41, v29
	v_fma_f32 v25, -v103, v40, v25
	v_fma_f32 v31, -v110, v47, v31
	v_fma_f32 v30, -v109, v46, v30
	v_fma_f32 v29, -v108, v45, v29
	v_fma_f32 v25, -v107, v44, v25
	s_waitcnt lgkmcnt(1)
	v_fma_f32 v31, -v114, v51, v31
	v_fma_f32 v30, -v113, v50, v30
	v_fma_f32 v29, -v112, v49, v29
	v_fma_f32 v25, -v111, v48, v25
	s_waitcnt lgkmcnt(0)
	v_fma_f32 v31, -v118, v55, v31
	v_fma_f32 v30, -v117, v54, v30
	v_fma_f32 v29, -v116, v53, v29
	v_fma_f32 v25, -v115, v52, v25
	v_fma_f32 v25, -v58, v119, v25
	v_add_u32_e32 v24, v56, v97
	v_add_f32_e32 v25, v29, v25
	v_add_f32_e32 v28, v30, v31
	v_add_f32_e32 v120, v28, v25
	v_add_u32_e32 v25, v24, v97
	ds_read_b128 v[28:31], v92 offset:7680
	ds_read_u16 v24, v24
	ds_read_b128 v[32:35], v92 offset:7696
	ds_read_b128 v[36:39], v92 offset:7712
	ds_read_b128 v[40:43], v92 offset:7728
	ds_read_b128 v[44:47], v92 offset:7744
	s_waitcnt lgkmcnt(4)
	v_lshlrev_b32_e32 v24, 16, v24
	v_mul_f32_e32 v28, v89, v28
	v_fma_f32 v31, -v93, v31, 0
	ds_read_b128 v[48:51], v92 offset:7760
	v_fma_f32 v30, -v91, v30, 0
	v_fma_f32 v29, -v90, v29, 0
	v_fma_f32 v24, v26, v24, -v28
	s_waitcnt lgkmcnt(4)
	v_fma_f32 v31, -v98, v35, v31
	ds_read_b128 v[52:55], v92 offset:7776
	v_fma_f32 v30, -v96, v34, v30
	v_fma_f32 v29, -v95, v33, v29
	v_fma_f32 v24, -v94, v32, v24
	s_waitcnt lgkmcnt(4)
	v_fma_f32 v31, -v102, v39, v31
	ds_read_b128 v[56:59], v92 offset:7792
	v_fma_f32 v30, -v101, v38, v30
	v_fma_f32 v29, -v100, v37, v29
	v_fma_f32 v24, -v99, v36, v24
	s_waitcnt lgkmcnt(4)
	v_fma_f32 v31, -v106, v43, v31
	v_fma_f32 v30, -v105, v42, v30
	v_fma_f32 v29, -v104, v41, v29
	v_fma_f32 v24, -v103, v40, v24
	s_waitcnt lgkmcnt(3)
	v_fma_f32 v31, -v110, v47, v31
	v_fma_f32 v30, -v109, v46, v30
	v_fma_f32 v29, -v108, v45, v29
	v_fma_f32 v24, -v107, v44, v24
	s_waitcnt lgkmcnt(2)
	v_fma_f32 v31, -v114, v51, v31
	v_fma_f32 v30, -v113, v50, v30
	v_fma_f32 v29, -v112, v49, v29
	v_fma_f32 v24, -v111, v48, v24
	s_waitcnt lgkmcnt(1)
	v_fma_f32 v31, -v118, v55, v31
	v_fma_f32 v30, -v117, v54, v30
	v_fma_f32 v29, -v116, v53, v29
	v_fma_f32 v24, -v115, v52, v24
	s_waitcnt lgkmcnt(0)
	v_fma_f32 v29, -v57, v120, v29
	v_fma_f32 v24, -v119, v56, v24
	v_add_f32_e32 v24, v29, v24
	v_add_f32_e32 v26, v30, v31
	v_add_u32_e32 v60, v25, v97
	ds_read_b128 v[28:31], v92 offset:7936
	ds_read_u16 v25, v25
	ds_read_b128 v[32:35], v92 offset:7952
	ds_read_b128 v[36:39], v92 offset:7968
	ds_read_b128 v[40:43], v92 offset:7984
	ds_read_b128 v[44:47], v92 offset:8000
	s_waitcnt lgkmcnt(4)
	v_lshlrev_b32_e32 v25, 16, v25
	v_mul_f32_e32 v28, v89, v28
	v_add_f32_e32 v121, v26, v24
	v_fma_f32 v24, -v93, v31, 0
	ds_read_b128 v[48:51], v92 offset:8016
	v_fma_f32 v26, -v91, v30, 0
	v_fma_f32 v29, -v90, v29, 0
	v_fma_f32 v25, v27, v25, -v28
	s_waitcnt lgkmcnt(4)
	v_fma_f32 v24, -v98, v35, v24
	ds_read_b128 v[52:55], v92 offset:8032
	v_fma_f32 v26, -v96, v34, v26
	v_fma_f32 v29, -v95, v33, v29
	v_fma_f32 v25, -v94, v32, v25
	s_waitcnt lgkmcnt(4)
	v_fma_f32 v24, -v102, v39, v24
	ds_read_b128 v[56:59], v92 offset:8048
	v_fma_f32 v26, -v101, v38, v26
	v_fma_f32 v29, -v100, v37, v29
	v_fma_f32 v25, -v99, v36, v25
	s_waitcnt lgkmcnt(4)
	v_fma_f32 v24, -v106, v43, v24
	v_fma_f32 v26, -v105, v42, v26
	v_fma_f32 v29, -v104, v41, v29
	v_fma_f32 v25, -v103, v40, v25
	s_waitcnt lgkmcnt(3)
	v_fma_f32 v24, -v110, v47, v24
	v_fma_f32 v26, -v109, v46, v26
	v_fma_f32 v29, -v108, v45, v29
	v_fma_f32 v25, -v107, v44, v25
	s_waitcnt lgkmcnt(2)
	v_fma_f32 v24, -v114, v51, v24
	v_fma_f32 v26, -v113, v50, v26
	v_fma_f32 v29, -v112, v49, v29
	v_fma_f32 v25, -v111, v48, v25
	s_waitcnt lgkmcnt(1)
	v_fma_f32 v24, -v118, v55, v24
	v_fma_f32 v26, -v117, v54, v26
	v_fma_f32 v29, -v116, v53, v29
	v_fma_f32 v25, -v115, v52, v25
	s_waitcnt lgkmcnt(0)
	v_fma_f32 v26, -v58, v121, v26
	v_fma_f32 v29, -v120, v57, v29
	v_fma_f32 v25, -v119, v56, v25
	v_add_f32_e32 v25, v29, v25
	v_add_f32_e32 v24, v24, v26
	v_add_f32_e32 v122, v24, v25
	ds_read_b128 v[24:27], v92 offset:8192
	ds_read_b128 v[28:31], v92 offset:8208
	ds_read_b128 v[32:35], v92 offset:8224
	ds_read_b128 v[36:39], v92 offset:8240
	ds_read_b128 v[40:43], v92 offset:8256
	s_waitcnt lgkmcnt(4)
	v_fma_f32 v27, -v93, v27, 0
	ds_read_b128 v[44:47], v92 offset:8272
	v_fma_f32 v26, -v91, v26, 0
	s_waitcnt lgkmcnt(4)
	v_fma_f32 v27, -v98, v31, v27
	ds_read_b128 v[48:51], v92 offset:8288
	v_fma_f32 v26, -v96, v30, v26
	s_waitcnt lgkmcnt(4)
	v_fma_f32 v27, -v102, v35, v27
	ds_read_b128 v[52:55], v92 offset:8304
	v_fma_f32 v26, -v101, v34, v26
	s_waitcnt lgkmcnt(4)
	v_fma_f32 v27, -v106, v39, v27
	v_fma_f32 v26, -v105, v38, v26
	s_waitcnt lgkmcnt(3)
	v_fma_f32 v27, -v110, v43, v27
	v_fma_f32 v26, -v109, v42, v26
	s_waitcnt lgkmcnt(2)
	v_fma_f32 v27, -v114, v47, v27
	v_fma_f32 v26, -v113, v46, v26
	s_waitcnt lgkmcnt(1)
	v_fma_f32 v27, -v118, v51, v27
	v_fma_f32 v26, -v117, v50, v26
	v_fma_f32 v25, -v90, v25, 0
	s_waitcnt lgkmcnt(0)
	v_fma_f32 v27, -v55, v122, v27
	v_fma_f32 v26, -v121, v54, v26
	v_fma_f32 v25, -v95, v29, v25
	ds_read_b128 v[54:57], v84 offset:128
	ds_read_u16 v29, v60
	v_mul_f32_e32 v24, v89, v24
	v_fma_f32 v25, -v100, v33, v25
	v_fma_f32 v25, -v104, v37, v25
	v_fma_f32 v25, -v108, v41, v25
	s_waitcnt lgkmcnt(0)
	v_lshlrev_b32_e32 v29, 16, v29
	v_fma_f32 v24, v54, v29, -v24
	v_fma_f32 v24, -v94, v28, v24
	v_fma_f32 v24, -v99, v32, v24
	v_fma_f32 v24, -v103, v36, v24
	v_fma_f32 v24, -v107, v40, v24
	v_fma_f32 v25, -v112, v45, v25
	v_fma_f32 v24, -v111, v44, v24
	v_fma_f32 v25, -v116, v49, v25
	v_fma_f32 v24, -v115, v48, v24
	v_fma_f32 v25, -v120, v53, v25
	v_fma_f32 v24, -v119, v52, v24
	v_add_f32_e32 v24, v25, v24
	v_add_f32_e32 v25, v26, v27
	v_add_f32_e32 v123, v25, v24
	ds_read_b128 v[24:27], v92 offset:8448
	ds_read_b128 v[28:31], v92 offset:8464
	v_add_u32_e32 v66, v60, v97
	ds_read_b128 v[32:35], v92 offset:8480
	ds_read_b128 v[36:39], v92 offset:8496
	s_waitcnt lgkmcnt(3)
	v_fma_f32 v25, -v90, v25, 0
	s_waitcnt lgkmcnt(2)
	v_fma_f32 v25, -v95, v29, v25
	ds_read_u16 v29, v66
	ds_read_b128 v[40:43], v92 offset:8512
	v_mul_f32_e32 v24, v89, v24
	v_fma_f32 v27, -v93, v27, 0
	ds_read_b128 v[44:47], v92 offset:8528
	s_waitcnt lgkmcnt(2)
	v_lshlrev_b32_e32 v29, 16, v29
	v_fma_f32 v26, -v91, v26, 0
	v_fma_f32 v24, v55, v29, -v24
	v_fma_f32 v27, -v98, v31, v27
	ds_read_b128 v[48:51], v92 offset:8544
	v_fma_f32 v26, -v96, v30, v26
	v_fma_f32 v24, -v94, v28, v24
	v_fma_f32 v27, -v102, v35, v27
	ds_read_b128 v[58:61], v92 offset:8560
	ds_read_b128 v[62:65], v92 offset:8576
	v_fma_f32 v26, -v101, v34, v26
	v_fma_f32 v25, -v100, v33, v25
	v_fma_f32 v24, -v99, v32, v24
	v_fma_f32 v27, -v106, v39, v27
	v_fma_f32 v26, -v105, v38, v26
	v_fma_f32 v25, -v104, v37, v25
	v_fma_f32 v24, -v103, v36, v24
	s_waitcnt lgkmcnt(4)
	v_fma_f32 v27, -v110, v43, v27
	v_fma_f32 v26, -v109, v42, v26
	v_fma_f32 v25, -v108, v41, v25
	v_fma_f32 v24, -v107, v40, v24
	s_waitcnt lgkmcnt(3)
	v_fma_f32 v27, -v114, v47, v27
	v_fma_f32 v26, -v113, v46, v26
	v_fma_f32 v25, -v112, v45, v25
	v_fma_f32 v24, -v111, v44, v24
	s_waitcnt lgkmcnt(2)
	v_fma_f32 v27, -v118, v51, v27
	v_fma_f32 v26, -v117, v50, v26
	v_fma_f32 v25, -v116, v49, v25
	v_fma_f32 v24, -v115, v48, v24
	s_waitcnt lgkmcnt(1)
	v_fma_f32 v27, -v122, v61, v27
	v_fma_f32 v26, -v121, v60, v26
	v_fma_f32 v25, -v120, v59, v25
	v_fma_f32 v24, -v119, v58, v24
	s_waitcnt lgkmcnt(0)
	v_fma_f32 v24, -v62, v123, v24
	v_add_f32_e32 v24, v25, v24
	v_add_f32_e32 v25, v26, v27
	v_add_f32_e32 v124, v25, v24
	ds_read_b128 v[24:27], v92 offset:8704
	ds_read_b128 v[28:31], v92 offset:8720
	v_add_u32_e32 v67, v66, v97
	ds_read_b128 v[32:35], v92 offset:8736
	ds_read_b128 v[36:39], v92 offset:8752
	s_waitcnt lgkmcnt(3)
	v_fma_f32 v25, -v90, v25, 0
	s_waitcnt lgkmcnt(2)
	v_fma_f32 v25, -v95, v29, v25
	ds_read_u16 v29, v67
	ds_read_b128 v[40:43], v92 offset:8768
	v_mul_f32_e32 v24, v89, v24
	v_fma_f32 v27, -v93, v27, 0
	ds_read_b128 v[44:47], v92 offset:8784
	s_waitcnt lgkmcnt(2)
	v_lshlrev_b32_e32 v29, 16, v29
	v_fma_f32 v26, -v91, v26, 0
	v_fma_f32 v24, v56, v29, -v24
	v_fma_f32 v27, -v98, v31, v27
	ds_read_b128 v[48:51], v92 offset:8800
	v_fma_f32 v26, -v96, v30, v26
	v_fma_f32 v24, -v94, v28, v24
	v_fma_f32 v27, -v102, v35, v27
	ds_read_b128 v[52:55], v92 offset:8816
	v_fma_f32 v26, -v101, v34, v26
	v_fma_f32 v25, -v100, v33, v25
	v_fma_f32 v24, -v99, v32, v24
	v_fma_f32 v27, -v106, v39, v27
	ds_read_b128 v[58:61], v92 offset:8832
	v_fma_f32 v26, -v105, v38, v26
	v_fma_f32 v25, -v104, v37, v25
	v_fma_f32 v24, -v103, v36, v24
	s_waitcnt lgkmcnt(4)
	v_fma_f32 v27, -v110, v43, v27
	v_fma_f32 v26, -v109, v42, v26
	v_fma_f32 v25, -v108, v41, v25
	v_fma_f32 v24, -v107, v40, v24
	s_waitcnt lgkmcnt(3)
	v_fma_f32 v27, -v114, v47, v27
	v_fma_f32 v26, -v113, v46, v26
	v_fma_f32 v25, -v112, v45, v25
	v_fma_f32 v24, -v111, v44, v24
	s_waitcnt lgkmcnt(2)
	v_fma_f32 v27, -v118, v51, v27
	v_fma_f32 v26, -v117, v50, v26
	v_fma_f32 v25, -v116, v49, v25
	v_fma_f32 v24, -v115, v48, v24
	s_waitcnt lgkmcnt(1)
	v_fma_f32 v27, -v122, v55, v27
	v_fma_f32 v26, -v121, v54, v26
	v_fma_f32 v25, -v120, v53, v25
	v_fma_f32 v24, -v119, v52, v24
	s_waitcnt lgkmcnt(0)
	v_fma_f32 v25, -v59, v124, v25
	v_fma_f32 v24, -v123, v58, v24
	v_add_f32_e32 v24, v25, v24
	v_add_f32_e32 v25, v26, v27
	v_add_f32_e32 v125, v25, v24
	ds_read_b128 v[24:27], v92 offset:8960
	ds_read_b128 v[28:31], v92 offset:8976
	v_add_u32_e32 v62, v67, v97
	ds_read_b128 v[32:35], v92 offset:8992
	ds_read_b128 v[36:39], v92 offset:9008
	s_waitcnt lgkmcnt(3)
	v_fma_f32 v25, -v90, v25, 0
	s_waitcnt lgkmcnt(2)
	v_fma_f32 v25, -v95, v29, v25
	ds_read_u16 v29, v62
	ds_read_b128 v[40:43], v92 offset:9024
	v_mul_f32_e32 v24, v89, v24
	v_fma_f32 v27, -v93, v27, 0
	ds_read_b128 v[44:47], v92 offset:9040
	s_waitcnt lgkmcnt(2)
	v_lshlrev_b32_e32 v29, 16, v29
	v_fma_f32 v26, -v91, v26, 0
	v_fma_f32 v24, v57, v29, -v24
	v_fma_f32 v27, -v98, v31, v27
	ds_read_b128 v[48:51], v92 offset:9056
	v_fma_f32 v26, -v96, v30, v26
	v_fma_f32 v24, -v94, v28, v24
	v_fma_f32 v27, -v102, v35, v27
	ds_read_b128 v[52:55], v92 offset:9072
	v_fma_f32 v26, -v101, v34, v26
	v_fma_f32 v25, -v100, v33, v25
	v_fma_f32 v24, -v99, v32, v24
	v_fma_f32 v27, -v106, v39, v27
	ds_read_b128 v[58:61], v92 offset:9088
	v_fma_f32 v26, -v105, v38, v26
	v_fma_f32 v25, -v104, v37, v25
	v_fma_f32 v24, -v103, v36, v24
	s_waitcnt lgkmcnt(4)
	v_fma_f32 v27, -v110, v43, v27
	v_fma_f32 v26, -v109, v42, v26
	v_fma_f32 v25, -v108, v41, v25
	v_fma_f32 v24, -v107, v40, v24
	s_waitcnt lgkmcnt(3)
	v_fma_f32 v27, -v114, v47, v27
	v_fma_f32 v26, -v113, v46, v26
	v_fma_f32 v25, -v112, v45, v25
	v_fma_f32 v24, -v111, v44, v24
	s_waitcnt lgkmcnt(2)
	v_fma_f32 v27, -v118, v51, v27
	v_fma_f32 v26, -v117, v50, v26
	v_fma_f32 v25, -v116, v49, v25
	v_fma_f32 v24, -v115, v48, v24
	s_waitcnt lgkmcnt(1)
	v_fma_f32 v27, -v122, v55, v27
	v_fma_f32 v26, -v121, v54, v26
	v_fma_f32 v25, -v120, v53, v25
	v_fma_f32 v24, -v119, v52, v24
	s_waitcnt lgkmcnt(0)
	v_fma_f32 v26, -v60, v125, v26
	v_fma_f32 v25, -v124, v59, v25
	v_fma_f32 v24, -v123, v58, v24
	v_add_f32_e32 v24, v25, v24
	v_add_f32_e32 v25, v27, v26
	v_add_f32_e32 v126, v25, v24
	ds_read_b128 v[24:27], v92 offset:9216
	ds_read_b128 v[28:31], v92 offset:9232
	ds_read_b128 v[32:35], v92 offset:9248
	ds_read_b128 v[36:39], v92 offset:9264
	ds_read_b128 v[40:43], v92 offset:9280
	s_waitcnt lgkmcnt(4)
	v_fma_f32 v27, -v93, v27, 0
	ds_read_b128 v[44:47], v92 offset:9296
	v_fma_f32 v26, -v91, v26, 0
	s_waitcnt lgkmcnt(4)
	v_fma_f32 v27, -v98, v31, v27
	ds_read_b128 v[48:51], v92 offset:9312
	v_fma_f32 v26, -v96, v30, v26
	s_waitcnt lgkmcnt(4)
	v_fma_f32 v27, -v102, v35, v27
	ds_read_b128 v[52:55], v92 offset:9328
	v_fma_f32 v26, -v101, v34, v26
	s_waitcnt lgkmcnt(4)
	v_fma_f32 v27, -v106, v39, v27
	ds_read_b128 v[56:59], v92 offset:9344
	v_fma_f32 v26, -v105, v38, v26
	s_waitcnt lgkmcnt(4)
	v_fma_f32 v27, -v110, v43, v27
	v_fma_f32 v26, -v109, v42, v26
	s_waitcnt lgkmcnt(3)
	v_fma_f32 v27, -v114, v47, v27
	v_fma_f32 v26, -v113, v46, v26
	s_waitcnt lgkmcnt(2)
	v_fma_f32 v27, -v118, v51, v27
	v_fma_f32 v26, -v117, v50, v26
	s_waitcnt lgkmcnt(1)
	v_fma_f32 v27, -v122, v55, v27
	v_fma_f32 v26, -v121, v54, v26
	v_fma_f32 v25, -v90, v25, 0
	v_add_u32_e32 v63, v62, v97
	s_waitcnt lgkmcnt(0)
	v_fma_f32 v27, -v59, v126, v27
	v_fma_f32 v26, -v125, v58, v26
	v_fma_f32 v25, -v95, v29, v25
	ds_read_b128 v[58:61], v84 offset:144
	ds_read_u16 v29, v63
	v_mul_f32_e32 v24, v89, v24
	v_fma_f32 v25, -v100, v33, v25
	v_fma_f32 v25, -v104, v37, v25
	v_fma_f32 v25, -v108, v41, v25
	s_waitcnt lgkmcnt(0)
	v_lshlrev_b32_e32 v29, 16, v29
	v_fma_f32 v24, v58, v29, -v24
	v_fma_f32 v24, -v94, v28, v24
	v_fma_f32 v24, -v99, v32, v24
	v_fma_f32 v24, -v103, v36, v24
	v_fma_f32 v24, -v107, v40, v24
	v_fma_f32 v25, -v112, v45, v25
	v_fma_f32 v24, -v111, v44, v24
	v_fma_f32 v25, -v116, v49, v25
	v_fma_f32 v24, -v115, v48, v24
	v_fma_f32 v25, -v120, v53, v25
	v_fma_f32 v24, -v119, v52, v24
	v_fma_f32 v25, -v124, v57, v25
	v_fma_f32 v24, -v123, v56, v24
	v_add_f32_e32 v24, v25, v24
	v_add_f32_e32 v25, v26, v27
	v_add_f32_e32 v127, v25, v24
	ds_read_b128 v[24:27], v92 offset:9472
	ds_read_b128 v[28:31], v92 offset:9488
	v_add_u32_e32 v62, v63, v97
	ds_read_b128 v[32:35], v92 offset:9504
	ds_read_b128 v[36:39], v92 offset:9520
	s_waitcnt lgkmcnt(3)
	v_fma_f32 v25, -v90, v25, 0
	s_waitcnt lgkmcnt(2)
	v_fma_f32 v25, -v95, v29, v25
	ds_read_u16 v29, v62
	ds_read_b128 v[40:43], v92 offset:9536
	v_mul_f32_e32 v24, v89, v24
	v_fma_f32 v27, -v93, v27, 0
	ds_read_b128 v[44:47], v92 offset:9552
	s_waitcnt lgkmcnt(2)
	v_lshlrev_b32_e32 v29, 16, v29
	v_fma_f32 v26, -v91, v26, 0
	v_fma_f32 v24, v59, v29, -v24
	v_fma_f32 v27, -v98, v31, v27
	ds_read_b128 v[48:51], v92 offset:9568
	v_fma_f32 v26, -v96, v30, v26
	v_fma_f32 v24, -v94, v28, v24
	v_fma_f32 v27, -v102, v35, v27
	ds_read_b128 v[52:55], v92 offset:9584
	v_fma_f32 v26, -v101, v34, v26
	v_fma_f32 v25, -v100, v33, v25
	v_fma_f32 v24, -v99, v32, v24
	v_fma_f32 v27, -v106, v39, v27
	ds_read_b128 v[64:67], v92 offset:9600
	ds_read_b128 v[68:71], v92 offset:9616
	v_fma_f32 v26, -v105, v38, v26
	v_fma_f32 v25, -v104, v37, v25
	v_fma_f32 v24, -v103, v36, v24
	s_waitcnt lgkmcnt(5)
	v_fma_f32 v27, -v110, v43, v27
	v_fma_f32 v26, -v109, v42, v26
	v_fma_f32 v25, -v108, v41, v25
	v_fma_f32 v24, -v107, v40, v24
	s_waitcnt lgkmcnt(4)
	v_fma_f32 v27, -v114, v47, v27
	v_fma_f32 v26, -v113, v46, v26
	v_fma_f32 v25, -v112, v45, v25
	v_fma_f32 v24, -v111, v44, v24
	s_waitcnt lgkmcnt(3)
	v_fma_f32 v27, -v118, v51, v27
	v_fma_f32 v26, -v117, v50, v26
	v_fma_f32 v25, -v116, v49, v25
	v_fma_f32 v24, -v115, v48, v24
	s_waitcnt lgkmcnt(2)
	v_fma_f32 v27, -v122, v55, v27
	v_fma_f32 v26, -v121, v54, v26
	v_fma_f32 v25, -v120, v53, v25
	v_fma_f32 v24, -v119, v52, v24
	s_waitcnt lgkmcnt(1)
	v_fma_f32 v27, -v126, v67, v27
	v_fma_f32 v26, -v125, v66, v26
	v_fma_f32 v25, -v124, v65, v25
	v_fma_f32 v24, -v123, v64, v24
	s_waitcnt lgkmcnt(0)
	v_fma_f32 v24, -v68, v127, v24
	v_add_f32_e32 v24, v25, v24
	v_add_f32_e32 v25, v26, v27
	v_add_f32_e32 v133, v25, v24
	ds_read_b128 v[24:27], v92 offset:9728
	ds_read_b128 v[28:31], v92 offset:9744
	v_add_u32_e32 v72, v62, v97
	ds_read_b128 v[32:35], v92 offset:9760
	ds_read_b128 v[36:39], v92 offset:9776
	s_waitcnt lgkmcnt(3)
	v_fma_f32 v25, -v90, v25, 0
	s_waitcnt lgkmcnt(2)
	v_fma_f32 v25, -v95, v29, v25
	ds_read_u16 v29, v72
	ds_read_b128 v[40:43], v92 offset:9792
	v_mul_f32_e32 v24, v89, v24
	v_fma_f32 v27, -v93, v27, 0
	ds_read_b128 v[44:47], v92 offset:9808
	s_waitcnt lgkmcnt(2)
	v_lshlrev_b32_e32 v29, 16, v29
	v_fma_f32 v26, -v91, v26, 0
	v_fma_f32 v24, v60, v29, -v24
	v_fma_f32 v27, -v98, v31, v27
	ds_read_b128 v[48:51], v92 offset:9824
	v_fma_f32 v26, -v96, v30, v26
	v_fma_f32 v24, -v94, v28, v24
	v_fma_f32 v27, -v102, v35, v27
	ds_read_b128 v[52:55], v92 offset:9840
	v_fma_f32 v26, -v101, v34, v26
	v_fma_f32 v25, -v100, v33, v25
	v_fma_f32 v24, -v99, v32, v24
	v_fma_f32 v27, -v106, v39, v27
	ds_read_b128 v[56:59], v92 offset:9856
	v_fma_f32 v26, -v105, v38, v26
	v_fma_f32 v25, -v104, v37, v25
	v_fma_f32 v24, -v103, v36, v24
	s_waitcnt lgkmcnt(4)
	v_fma_f32 v27, -v110, v43, v27
	ds_read_b128 v[62:65], v92 offset:9872
	v_fma_f32 v26, -v109, v42, v26
	v_fma_f32 v25, -v108, v41, v25
	v_fma_f32 v24, -v107, v40, v24
	s_waitcnt lgkmcnt(4)
	v_fma_f32 v27, -v114, v47, v27
	v_fma_f32 v26, -v113, v46, v26
	v_fma_f32 v25, -v112, v45, v25
	v_fma_f32 v24, -v111, v44, v24
	s_waitcnt lgkmcnt(3)
	v_fma_f32 v27, -v118, v51, v27
	v_fma_f32 v26, -v117, v50, v26
	v_fma_f32 v25, -v116, v49, v25
	v_fma_f32 v24, -v115, v48, v24
	s_waitcnt lgkmcnt(2)
	v_fma_f32 v27, -v122, v55, v27
	v_fma_f32 v26, -v121, v54, v26
	v_fma_f32 v25, -v120, v53, v25
	v_fma_f32 v24, -v119, v52, v24
	s_waitcnt lgkmcnt(1)
	v_fma_f32 v27, -v126, v59, v27
	v_fma_f32 v26, -v125, v58, v26
	v_fma_f32 v25, -v124, v57, v25
	v_fma_f32 v24, -v123, v56, v24
	s_waitcnt lgkmcnt(0)
	v_fma_f32 v25, -v63, v133, v25
	v_fma_f32 v24, -v127, v62, v24
	v_add_f32_e32 v24, v25, v24
	v_add_f32_e32 v25, v26, v27
	v_add_f32_e32 v134, v25, v24
	ds_read_b128 v[24:27], v92 offset:9984
	ds_read_b128 v[28:31], v92 offset:10000
	v_add_u32_e32 v66, v72, v97
	ds_read_b128 v[32:35], v92 offset:10016
	ds_read_b128 v[36:39], v92 offset:10032
	s_waitcnt lgkmcnt(3)
	v_fma_f32 v25, -v90, v25, 0
	s_waitcnt lgkmcnt(2)
	v_fma_f32 v25, -v95, v29, v25
	ds_read_u16 v29, v66
	ds_read_b128 v[40:43], v92 offset:10048
	v_mul_f32_e32 v24, v89, v24
	v_fma_f32 v27, -v93, v27, 0
	ds_read_b128 v[44:47], v92 offset:10064
	s_waitcnt lgkmcnt(2)
	v_lshlrev_b32_e32 v29, 16, v29
	v_fma_f32 v26, -v91, v26, 0
	v_fma_f32 v24, v61, v29, -v24
	v_fma_f32 v27, -v98, v31, v27
	ds_read_b128 v[48:51], v92 offset:10080
	v_fma_f32 v26, -v96, v30, v26
	v_fma_f32 v24, -v94, v28, v24
	v_fma_f32 v27, -v102, v35, v27
	ds_read_b128 v[52:55], v92 offset:10096
	v_fma_f32 v26, -v101, v34, v26
	v_fma_f32 v25, -v100, v33, v25
	v_fma_f32 v24, -v99, v32, v24
	v_fma_f32 v27, -v106, v39, v27
	ds_read_b128 v[56:59], v92 offset:10112
	v_fma_f32 v26, -v105, v38, v26
	v_fma_f32 v25, -v104, v37, v25
	v_fma_f32 v24, -v103, v36, v24
	s_waitcnt lgkmcnt(4)
	v_fma_f32 v27, -v110, v43, v27
	ds_read_b128 v[62:65], v92 offset:10128
	v_fma_f32 v26, -v109, v42, v26
	v_fma_f32 v25, -v108, v41, v25
	v_fma_f32 v24, -v107, v40, v24
	s_waitcnt lgkmcnt(4)
	v_fma_f32 v27, -v114, v47, v27
	v_fma_f32 v26, -v113, v46, v26
	v_fma_f32 v25, -v112, v45, v25
	v_fma_f32 v24, -v111, v44, v24
	s_waitcnt lgkmcnt(3)
	v_fma_f32 v27, -v118, v51, v27
	v_fma_f32 v26, -v117, v50, v26
	v_fma_f32 v25, -v116, v49, v25
	v_fma_f32 v24, -v115, v48, v24
	s_waitcnt lgkmcnt(2)
	v_fma_f32 v27, -v122, v55, v27
	v_fma_f32 v26, -v121, v54, v26
	v_fma_f32 v25, -v120, v53, v25
	v_fma_f32 v24, -v119, v52, v24
	s_waitcnt lgkmcnt(1)
	v_fma_f32 v27, -v126, v59, v27
	v_fma_f32 v26, -v125, v58, v26
	v_fma_f32 v25, -v124, v57, v25
	v_fma_f32 v24, -v123, v56, v24
	s_waitcnt lgkmcnt(0)
	v_fma_f32 v26, -v64, v134, v26
	v_fma_f32 v25, -v133, v63, v25
	v_fma_f32 v24, -v127, v62, v24
	v_add_f32_e32 v24, v25, v24
	v_add_f32_e32 v25, v27, v26
	v_add_f32_e32 v135, v25, v24
	ds_read_b128 v[24:27], v92 offset:10240
	ds_read_b128 v[28:31], v92 offset:10256
	ds_read_b128 v[32:35], v92 offset:10272
	ds_read_b128 v[36:39], v92 offset:10288
	ds_read_b128 v[40:43], v92 offset:10304
	s_waitcnt lgkmcnt(4)
	v_fma_f32 v27, -v93, v27, 0
	ds_read_b128 v[44:47], v92 offset:10320
	v_fma_f32 v26, -v91, v26, 0
	s_waitcnt lgkmcnt(4)
	v_fma_f32 v27, -v98, v31, v27
	ds_read_b128 v[48:51], v92 offset:10336
	v_fma_f32 v26, -v96, v30, v26
	s_waitcnt lgkmcnt(4)
	v_fma_f32 v27, -v102, v35, v27
	ds_read_b128 v[52:55], v92 offset:10352
	v_fma_f32 v26, -v101, v34, v26
	s_waitcnt lgkmcnt(4)
	v_fma_f32 v27, -v106, v39, v27
	ds_read_b128 v[56:59], v92 offset:10368
	v_fma_f32 v26, -v105, v38, v26
	s_waitcnt lgkmcnt(4)
	v_fma_f32 v27, -v110, v43, v27
	ds_read_b128 v[60:63], v92 offset:10384
	v_fma_f32 v26, -v109, v42, v26
	s_waitcnt lgkmcnt(4)
	v_fma_f32 v27, -v114, v47, v27
	v_fma_f32 v26, -v113, v46, v26
	s_waitcnt lgkmcnt(3)
	v_fma_f32 v27, -v118, v51, v27
	v_fma_f32 v26, -v117, v50, v26
	s_waitcnt lgkmcnt(2)
	v_fma_f32 v27, -v122, v55, v27
	v_fma_f32 v26, -v121, v54, v26
	s_waitcnt lgkmcnt(1)
	v_fma_f32 v27, -v126, v59, v27
	v_fma_f32 v26, -v125, v58, v26
	v_fma_f32 v25, -v90, v25, 0
	v_add_u32_e32 v67, v66, v97
	s_waitcnt lgkmcnt(0)
	v_fma_f32 v27, -v63, v135, v27
	v_fma_f32 v26, -v134, v62, v26
	v_fma_f32 v25, -v95, v29, v25
	ds_read_b128 v[62:65], v84 offset:160
	ds_read_u16 v29, v67
	v_mul_f32_e32 v24, v89, v24
	v_fma_f32 v25, -v100, v33, v25
	v_fma_f32 v25, -v104, v37, v25
	v_fma_f32 v25, -v108, v41, v25
	s_waitcnt lgkmcnt(0)
	v_lshlrev_b32_e32 v29, 16, v29
	v_fma_f32 v24, v62, v29, -v24
	v_fma_f32 v24, -v94, v28, v24
	v_fma_f32 v24, -v99, v32, v24
	v_fma_f32 v24, -v103, v36, v24
	v_fma_f32 v24, -v107, v40, v24
	v_fma_f32 v25, -v112, v45, v25
	v_fma_f32 v24, -v111, v44, v24
	v_fma_f32 v25, -v116, v49, v25
	v_fma_f32 v24, -v115, v48, v24
	v_fma_f32 v25, -v120, v53, v25
	v_fma_f32 v24, -v119, v52, v24
	v_fma_f32 v25, -v124, v57, v25
	v_fma_f32 v24, -v123, v56, v24
	v_fma_f32 v25, -v133, v61, v25
	v_fma_f32 v24, -v127, v60, v24
	v_add_f32_e32 v24, v25, v24
	v_add_f32_e32 v25, v26, v27
	v_add_f32_e32 v136, v25, v24
	ds_read_b128 v[24:27], v92 offset:10496
	ds_read_b128 v[28:31], v92 offset:10512
	v_add_u32_e32 v74, v67, v97
	ds_read_b128 v[32:35], v92 offset:10528
	ds_read_b128 v[36:39], v92 offset:10544
	s_waitcnt lgkmcnt(3)
	v_fma_f32 v25, -v90, v25, 0
	s_waitcnt lgkmcnt(2)
	v_fma_f32 v25, -v95, v29, v25
	ds_read_u16 v29, v74
	ds_read_b128 v[40:43], v92 offset:10560
	v_mul_f32_e32 v24, v89, v24
	v_fma_f32 v27, -v93, v27, 0
	ds_read_b128 v[44:47], v92 offset:10576
	s_waitcnt lgkmcnt(2)
	v_lshlrev_b32_e32 v29, 16, v29
	v_fma_f32 v26, -v91, v26, 0
	v_fma_f32 v24, v63, v29, -v24
	v_fma_f32 v27, -v98, v31, v27
	ds_read_b128 v[48:51], v92 offset:10592
	v_fma_f32 v26, -v96, v30, v26
	v_fma_f32 v24, -v94, v28, v24
	v_fma_f32 v27, -v102, v35, v27
	ds_read_b128 v[52:55], v92 offset:10608
	v_fma_f32 v26, -v101, v34, v26
	v_fma_f32 v25, -v100, v33, v25
	v_fma_f32 v24, -v99, v32, v24
	v_fma_f32 v27, -v106, v39, v27
	ds_read_b128 v[56:59], v92 offset:10624
	v_fma_f32 v26, -v105, v38, v26
	v_fma_f32 v25, -v104, v37, v25
	v_fma_f32 v24, -v103, v36, v24
	s_waitcnt lgkmcnt(4)
	v_fma_f32 v27, -v110, v43, v27
	ds_read_b128 v[66:69], v92 offset:10640
	ds_read_b128 v[70:73], v92 offset:10656
	v_fma_f32 v26, -v109, v42, v26
	v_fma_f32 v25, -v108, v41, v25
	v_fma_f32 v24, -v107, v40, v24
	s_waitcnt lgkmcnt(5)
	v_fma_f32 v27, -v114, v47, v27
	v_fma_f32 v26, -v113, v46, v26
	v_fma_f32 v25, -v112, v45, v25
	v_fma_f32 v24, -v111, v44, v24
	s_waitcnt lgkmcnt(4)
	v_fma_f32 v27, -v118, v51, v27
	v_fma_f32 v26, -v117, v50, v26
	v_fma_f32 v25, -v116, v49, v25
	v_fma_f32 v24, -v115, v48, v24
	s_waitcnt lgkmcnt(3)
	v_fma_f32 v27, -v122, v55, v27
	v_fma_f32 v26, -v121, v54, v26
	v_fma_f32 v25, -v120, v53, v25
	v_fma_f32 v24, -v119, v52, v24
	s_waitcnt lgkmcnt(2)
	v_fma_f32 v27, -v126, v59, v27
	v_fma_f32 v26, -v125, v58, v26
	v_fma_f32 v25, -v124, v57, v25
	v_fma_f32 v24, -v123, v56, v24
	s_waitcnt lgkmcnt(1)
	v_fma_f32 v27, -v135, v69, v27
	v_fma_f32 v26, -v134, v68, v26
	v_fma_f32 v25, -v133, v67, v25
	v_fma_f32 v24, -v127, v66, v24
	s_waitcnt lgkmcnt(0)
	v_fma_f32 v24, -v70, v136, v24
	v_add_f32_e32 v24, v25, v24
	v_add_f32_e32 v25, v26, v27
	v_add_f32_e32 v137, v25, v24
	ds_read_b128 v[24:27], v92 offset:10752
	ds_read_b128 v[28:31], v92 offset:10768
	v_add_u32_e32 v75, v74, v97
	ds_read_b128 v[32:35], v92 offset:10784
	ds_read_b128 v[36:39], v92 offset:10800
	s_waitcnt lgkmcnt(3)
	v_fma_f32 v25, -v90, v25, 0
	s_waitcnt lgkmcnt(2)
	v_fma_f32 v25, -v95, v29, v25
	ds_read_u16 v29, v75
	ds_read_b128 v[40:43], v92 offset:10816
	v_mul_f32_e32 v24, v89, v24
	v_fma_f32 v27, -v93, v27, 0
	ds_read_b128 v[44:47], v92 offset:10832
	s_waitcnt lgkmcnt(2)
	v_lshlrev_b32_e32 v29, 16, v29
	v_fma_f32 v26, -v91, v26, 0
	v_fma_f32 v24, v64, v29, -v24
	v_fma_f32 v27, -v98, v31, v27
	ds_read_b128 v[48:51], v92 offset:10848
	v_fma_f32 v26, -v96, v30, v26
	v_fma_f32 v24, -v94, v28, v24
	v_fma_f32 v27, -v102, v35, v27
	ds_read_b128 v[52:55], v92 offset:10864
	v_fma_f32 v26, -v101, v34, v26
	v_fma_f32 v25, -v100, v33, v25
	v_fma_f32 v24, -v99, v32, v24
	v_fma_f32 v27, -v106, v39, v27
	ds_read_b128 v[56:59], v92 offset:10880
	v_fma_f32 v26, -v105, v38, v26
	v_fma_f32 v25, -v104, v37, v25
	v_fma_f32 v24, -v103, v36, v24
	s_waitcnt lgkmcnt(4)
	v_fma_f32 v27, -v110, v43, v27
	ds_read_b128 v[60:63], v92 offset:10896
	v_fma_f32 v26, -v109, v42, v26
	v_fma_f32 v25, -v108, v41, v25
	v_fma_f32 v24, -v107, v40, v24
	s_waitcnt lgkmcnt(4)
	v_fma_f32 v27, -v114, v47, v27
	ds_read_b128 v[66:69], v92 offset:10912
	v_fma_f32 v26, -v113, v46, v26
	v_fma_f32 v25, -v112, v45, v25
	v_fma_f32 v24, -v111, v44, v24
	s_waitcnt lgkmcnt(4)
	v_fma_f32 v27, -v118, v51, v27
	v_fma_f32 v26, -v117, v50, v26
	v_fma_f32 v25, -v116, v49, v25
	v_fma_f32 v24, -v115, v48, v24
	s_waitcnt lgkmcnt(3)
	v_fma_f32 v27, -v122, v55, v27
	v_fma_f32 v26, -v121, v54, v26
	v_fma_f32 v25, -v120, v53, v25
	v_fma_f32 v24, -v119, v52, v24
	s_waitcnt lgkmcnt(2)
	v_fma_f32 v27, -v126, v59, v27
	v_fma_f32 v26, -v125, v58, v26
	v_fma_f32 v25, -v124, v57, v25
	v_fma_f32 v24, -v123, v56, v24
	s_waitcnt lgkmcnt(1)
	v_fma_f32 v27, -v135, v63, v27
	v_fma_f32 v26, -v134, v62, v26
	v_fma_f32 v25, -v133, v61, v25
	v_fma_f32 v24, -v127, v60, v24
	s_waitcnt lgkmcnt(0)
	v_fma_f32 v25, -v67, v137, v25
	v_fma_f32 v24, -v136, v66, v24
	v_add_f32_e32 v24, v25, v24
	v_add_f32_e32 v25, v26, v27
	v_add_f32_e32 v138, v25, v24
	ds_read_b128 v[24:27], v92 offset:11008
	ds_read_b128 v[28:31], v92 offset:11024
	v_add_u32_e32 v70, v75, v97
	ds_read_b128 v[32:35], v92 offset:11040
	ds_read_b128 v[36:39], v92 offset:11056
	s_waitcnt lgkmcnt(3)
	v_fma_f32 v25, -v90, v25, 0
	s_waitcnt lgkmcnt(2)
	v_fma_f32 v25, -v95, v29, v25
	ds_read_u16 v29, v70
	ds_read_b128 v[40:43], v92 offset:11072
	v_mul_f32_e32 v24, v89, v24
	v_fma_f32 v27, -v93, v27, 0
	ds_read_b128 v[44:47], v92 offset:11088
	s_waitcnt lgkmcnt(2)
	v_lshlrev_b32_e32 v29, 16, v29
	v_fma_f32 v26, -v91, v26, 0
	v_fma_f32 v24, v65, v29, -v24
	v_fma_f32 v27, -v98, v31, v27
	ds_read_b128 v[48:51], v92 offset:11104
	v_fma_f32 v26, -v96, v30, v26
	v_fma_f32 v24, -v94, v28, v24
	v_fma_f32 v27, -v102, v35, v27
	ds_read_b128 v[52:55], v92 offset:11120
	v_fma_f32 v26, -v101, v34, v26
	v_fma_f32 v25, -v100, v33, v25
	v_fma_f32 v24, -v99, v32, v24
	v_fma_f32 v27, -v106, v39, v27
	ds_read_b128 v[56:59], v92 offset:11136
	v_fma_f32 v26, -v105, v38, v26
	v_fma_f32 v25, -v104, v37, v25
	v_fma_f32 v24, -v103, v36, v24
	s_waitcnt lgkmcnt(4)
	v_fma_f32 v27, -v110, v43, v27
	ds_read_b128 v[60:63], v92 offset:11152
	v_fma_f32 v26, -v109, v42, v26
	v_fma_f32 v25, -v108, v41, v25
	v_fma_f32 v24, -v107, v40, v24
	s_waitcnt lgkmcnt(4)
	v_fma_f32 v27, -v114, v47, v27
	ds_read_b128 v[66:69], v92 offset:11168
	v_fma_f32 v26, -v113, v46, v26
	v_fma_f32 v25, -v112, v45, v25
	v_fma_f32 v24, -v111, v44, v24
	s_waitcnt lgkmcnt(4)
	v_fma_f32 v27, -v118, v51, v27
	v_fma_f32 v26, -v117, v50, v26
	v_fma_f32 v25, -v116, v49, v25
	v_fma_f32 v24, -v115, v48, v24
	s_waitcnt lgkmcnt(3)
	v_fma_f32 v27, -v122, v55, v27
	v_fma_f32 v26, -v121, v54, v26
	v_fma_f32 v25, -v120, v53, v25
	v_fma_f32 v24, -v119, v52, v24
	s_waitcnt lgkmcnt(2)
	v_fma_f32 v27, -v126, v59, v27
	v_fma_f32 v26, -v125, v58, v26
	v_fma_f32 v25, -v124, v57, v25
	v_fma_f32 v24, -v123, v56, v24
	s_waitcnt lgkmcnt(1)
	v_fma_f32 v27, -v135, v63, v27
	v_fma_f32 v26, -v134, v62, v26
	v_fma_f32 v25, -v133, v61, v25
	v_fma_f32 v24, -v127, v60, v24
	s_waitcnt lgkmcnt(0)
	v_fma_f32 v26, -v68, v138, v26
	v_fma_f32 v25, -v137, v67, v25
	v_fma_f32 v24, -v136, v66, v24
	v_add_f32_e32 v24, v25, v24
	v_add_f32_e32 v25, v27, v26
	v_add_f32_e32 v139, v25, v24
	ds_read_b128 v[24:27], v92 offset:11264
	ds_read_b128 v[28:31], v92 offset:11280
	ds_read_b128 v[32:35], v92 offset:11296
	ds_read_b128 v[36:39], v92 offset:11312
	ds_read_b128 v[40:43], v92 offset:11328
	s_waitcnt lgkmcnt(4)
	v_fma_f32 v27, -v93, v27, 0
	ds_read_b128 v[44:47], v92 offset:11344
	v_fma_f32 v26, -v91, v26, 0
	s_waitcnt lgkmcnt(4)
	v_fma_f32 v27, -v98, v31, v27
	ds_read_b128 v[48:51], v92 offset:11360
	v_fma_f32 v26, -v96, v30, v26
	s_waitcnt lgkmcnt(4)
	v_fma_f32 v27, -v102, v35, v27
	ds_read_b128 v[52:55], v92 offset:11376
	v_fma_f32 v26, -v101, v34, v26
	s_waitcnt lgkmcnt(4)
	v_fma_f32 v27, -v106, v39, v27
	ds_read_b128 v[56:59], v92 offset:11392
	v_fma_f32 v26, -v105, v38, v26
	s_waitcnt lgkmcnt(4)
	v_fma_f32 v27, -v110, v43, v27
	ds_read_b128 v[60:63], v92 offset:11408
	v_fma_f32 v26, -v109, v42, v26
	s_waitcnt lgkmcnt(4)
	v_fma_f32 v27, -v114, v47, v27
	ds_read_b128 v[64:67], v92 offset:11424
	v_fma_f32 v26, -v113, v46, v26
	s_waitcnt lgkmcnt(4)
	v_fma_f32 v27, -v118, v51, v27
	v_fma_f32 v26, -v117, v50, v26
	s_waitcnt lgkmcnt(3)
	v_fma_f32 v27, -v122, v55, v27
	v_fma_f32 v26, -v121, v54, v26
	s_waitcnt lgkmcnt(2)
	v_fma_f32 v27, -v126, v59, v27
	v_fma_f32 v26, -v125, v58, v26
	s_waitcnt lgkmcnt(1)
	v_fma_f32 v27, -v135, v63, v27
	v_fma_f32 v26, -v134, v62, v26
	v_fma_f32 v25, -v90, v25, 0
	v_add_u32_e32 v71, v70, v97
	s_waitcnt lgkmcnt(0)
	v_fma_f32 v27, -v67, v139, v27
	v_fma_f32 v26, -v138, v66, v26
	v_fma_f32 v25, -v95, v29, v25
	ds_read_b128 v[66:69], v84 offset:176
	ds_read_u16 v29, v71
	v_mul_f32_e32 v24, v89, v24
	v_fma_f32 v25, -v100, v33, v25
	v_fma_f32 v25, -v104, v37, v25
	v_fma_f32 v25, -v108, v41, v25
	s_waitcnt lgkmcnt(0)
	v_lshlrev_b32_e32 v29, 16, v29
	v_fma_f32 v24, v66, v29, -v24
	v_fma_f32 v24, -v94, v28, v24
	v_fma_f32 v24, -v99, v32, v24
	v_fma_f32 v24, -v103, v36, v24
	v_fma_f32 v24, -v107, v40, v24
	v_fma_f32 v25, -v112, v45, v25
	v_fma_f32 v24, -v111, v44, v24
	v_fma_f32 v25, -v116, v49, v25
	v_fma_f32 v24, -v115, v48, v24
	v_fma_f32 v25, -v120, v53, v25
	v_fma_f32 v24, -v119, v52, v24
	v_fma_f32 v25, -v124, v57, v25
	v_fma_f32 v24, -v123, v56, v24
	v_fma_f32 v25, -v133, v61, v25
	v_fma_f32 v24, -v127, v60, v24
	v_fma_f32 v25, -v137, v65, v25
	v_fma_f32 v24, -v136, v64, v24
	v_add_f32_e32 v24, v25, v24
	v_add_f32_e32 v25, v26, v27
	v_add_f32_e32 v140, v25, v24
	ds_read_b128 v[24:27], v92 offset:11520
	ds_read_b128 v[28:31], v92 offset:11536
	v_add_u32_e32 v70, v71, v97
	ds_read_b128 v[32:35], v92 offset:11552
	ds_read_b128 v[36:39], v92 offset:11568
	s_waitcnt lgkmcnt(3)
	v_fma_f32 v25, -v90, v25, 0
	s_waitcnt lgkmcnt(2)
	v_fma_f32 v25, -v95, v29, v25
	ds_read_u16 v29, v70
	ds_read_b128 v[40:43], v92 offset:11584
	v_mul_f32_e32 v24, v89, v24
	v_fma_f32 v27, -v93, v27, 0
	ds_read_b128 v[44:47], v92 offset:11600
	s_waitcnt lgkmcnt(2)
	v_lshlrev_b32_e32 v29, 16, v29
	v_fma_f32 v26, -v91, v26, 0
	v_fma_f32 v24, v67, v29, -v24
	v_fma_f32 v27, -v98, v31, v27
	ds_read_b128 v[48:51], v92 offset:11616
	v_fma_f32 v26, -v96, v30, v26
	v_fma_f32 v24, -v94, v28, v24
	v_fma_f32 v27, -v102, v35, v27
	ds_read_b128 v[52:55], v92 offset:11632
	v_fma_f32 v26, -v101, v34, v26
	v_fma_f32 v25, -v100, v33, v25
	v_fma_f32 v24, -v99, v32, v24
	v_fma_f32 v27, -v106, v39, v27
	ds_read_b128 v[56:59], v92 offset:11648
	v_fma_f32 v26, -v105, v38, v26
	v_fma_f32 v25, -v104, v37, v25
	v_fma_f32 v24, -v103, v36, v24
	s_waitcnt lgkmcnt(4)
	v_fma_f32 v27, -v110, v43, v27
	ds_read_b128 v[60:63], v92 offset:11664
	v_fma_f32 v26, -v109, v42, v26
	v_fma_f32 v25, -v108, v41, v25
	v_fma_f32 v24, -v107, v40, v24
	s_waitcnt lgkmcnt(4)
	v_fma_f32 v27, -v114, v47, v27
	ds_read_b128 v[72:75], v92 offset:11680
	ds_read_b128 v[76:79], v92 offset:11696
	v_fma_f32 v26, -v113, v46, v26
	v_fma_f32 v25, -v112, v45, v25
	v_fma_f32 v24, -v111, v44, v24
	s_waitcnt lgkmcnt(5)
	v_fma_f32 v27, -v118, v51, v27
	v_fma_f32 v26, -v117, v50, v26
	v_fma_f32 v25, -v116, v49, v25
	v_fma_f32 v24, -v115, v48, v24
	s_waitcnt lgkmcnt(4)
	v_fma_f32 v27, -v122, v55, v27
	v_fma_f32 v26, -v121, v54, v26
	v_fma_f32 v25, -v120, v53, v25
	v_fma_f32 v24, -v119, v52, v24
	s_waitcnt lgkmcnt(3)
	v_fma_f32 v27, -v126, v59, v27
	v_fma_f32 v26, -v125, v58, v26
	v_fma_f32 v25, -v124, v57, v25
	v_fma_f32 v24, -v123, v56, v24
	s_waitcnt lgkmcnt(2)
	v_fma_f32 v27, -v135, v63, v27
	v_fma_f32 v26, -v134, v62, v26
	v_fma_f32 v25, -v133, v61, v25
	v_fma_f32 v24, -v127, v60, v24
	s_waitcnt lgkmcnt(1)
	v_fma_f32 v27, -v139, v75, v27
	v_fma_f32 v26, -v138, v74, v26
	v_fma_f32 v25, -v137, v73, v25
	v_fma_f32 v24, -v136, v72, v24
	s_waitcnt lgkmcnt(0)
	v_fma_f32 v24, -v76, v140, v24
	v_add_f32_e32 v24, v25, v24
	v_add_f32_e32 v25, v26, v27
	v_add_f32_e32 v141, v25, v24
	ds_read_b128 v[24:27], v92 offset:11776
	ds_read_b128 v[28:31], v92 offset:11792
	v_add_u32_e32 v80, v70, v97
	ds_read_b128 v[32:35], v92 offset:11808
	ds_read_b128 v[36:39], v92 offset:11824
	s_waitcnt lgkmcnt(3)
	v_fma_f32 v25, -v90, v25, 0
	s_waitcnt lgkmcnt(2)
	v_fma_f32 v25, -v95, v29, v25
	ds_read_u16 v29, v80
	ds_read_b128 v[40:43], v92 offset:11840
	v_mul_f32_e32 v24, v89, v24
	v_fma_f32 v27, -v93, v27, 0
	ds_read_b128 v[44:47], v92 offset:11856
	s_waitcnt lgkmcnt(2)
	v_lshlrev_b32_e32 v29, 16, v29
	v_fma_f32 v26, -v91, v26, 0
	v_fma_f32 v24, v68, v29, -v24
	v_fma_f32 v27, -v98, v31, v27
	ds_read_b128 v[48:51], v92 offset:11872
	v_fma_f32 v26, -v96, v30, v26
	v_fma_f32 v24, -v94, v28, v24
	v_fma_f32 v27, -v102, v35, v27
	ds_read_b128 v[52:55], v92 offset:11888
	v_fma_f32 v26, -v101, v34, v26
	v_fma_f32 v25, -v100, v33, v25
	v_fma_f32 v24, -v99, v32, v24
	v_fma_f32 v27, -v106, v39, v27
	ds_read_b128 v[56:59], v92 offset:11904
	v_fma_f32 v26, -v105, v38, v26
	v_fma_f32 v25, -v104, v37, v25
	v_fma_f32 v24, -v103, v36, v24
	s_waitcnt lgkmcnt(4)
	v_fma_f32 v27, -v110, v43, v27
	ds_read_b128 v[60:63], v92 offset:11920
	v_fma_f32 v26, -v109, v42, v26
	v_fma_f32 v25, -v108, v41, v25
	v_fma_f32 v24, -v107, v40, v24
	s_waitcnt lgkmcnt(4)
	v_fma_f32 v27, -v114, v47, v27
	ds_read_b128 v[64:67], v92 offset:11936
	v_fma_f32 v26, -v113, v46, v26
	v_fma_f32 v25, -v112, v45, v25
	v_fma_f32 v24, -v111, v44, v24
	s_waitcnt lgkmcnt(4)
	v_fma_f32 v27, -v118, v51, v27
	ds_read_b128 v[70:73], v92 offset:11952
	v_fma_f32 v26, -v117, v50, v26
	v_fma_f32 v25, -v116, v49, v25
	v_fma_f32 v24, -v115, v48, v24
	s_waitcnt lgkmcnt(4)
	v_fma_f32 v27, -v122, v55, v27
	v_fma_f32 v26, -v121, v54, v26
	v_fma_f32 v25, -v120, v53, v25
	v_fma_f32 v24, -v119, v52, v24
	s_waitcnt lgkmcnt(3)
	v_fma_f32 v27, -v126, v59, v27
	v_fma_f32 v26, -v125, v58, v26
	v_fma_f32 v25, -v124, v57, v25
	v_fma_f32 v24, -v123, v56, v24
	s_waitcnt lgkmcnt(2)
	v_fma_f32 v27, -v135, v63, v27
	v_fma_f32 v26, -v134, v62, v26
	v_fma_f32 v25, -v133, v61, v25
	v_fma_f32 v24, -v127, v60, v24
	s_waitcnt lgkmcnt(1)
	v_fma_f32 v27, -v139, v67, v27
	v_fma_f32 v26, -v138, v66, v26
	v_fma_f32 v25, -v137, v65, v25
	v_fma_f32 v24, -v136, v64, v24
	s_waitcnt lgkmcnt(0)
	v_fma_f32 v25, -v71, v141, v25
	v_fma_f32 v24, -v140, v70, v24
	v_add_f32_e32 v24, v25, v24
	v_add_f32_e32 v25, v26, v27
	v_add_f32_e32 v142, v25, v24
	ds_read_b128 v[24:27], v92 offset:12032
	ds_read_b128 v[28:31], v92 offset:12048
	v_add_u32_e32 v74, v80, v97
	ds_read_b128 v[32:35], v92 offset:12064
	ds_read_b128 v[36:39], v92 offset:12080
	s_waitcnt lgkmcnt(3)
	v_fma_f32 v25, -v90, v25, 0
	s_waitcnt lgkmcnt(2)
	v_fma_f32 v25, -v95, v29, v25
	ds_read_u16 v29, v74
	ds_read_b128 v[40:43], v92 offset:12096
	v_mul_f32_e32 v24, v89, v24
	v_fma_f32 v27, -v93, v27, 0
	ds_read_b128 v[44:47], v92 offset:12112
	s_waitcnt lgkmcnt(2)
	v_lshlrev_b32_e32 v29, 16, v29
	v_fma_f32 v26, -v91, v26, 0
	v_fma_f32 v24, v69, v29, -v24
	v_fma_f32 v27, -v98, v31, v27
	ds_read_b128 v[48:51], v92 offset:12128
	v_fma_f32 v26, -v96, v30, v26
	v_fma_f32 v24, -v94, v28, v24
	v_fma_f32 v27, -v102, v35, v27
	ds_read_b128 v[52:55], v92 offset:12144
	v_fma_f32 v26, -v101, v34, v26
	v_fma_f32 v25, -v100, v33, v25
	v_fma_f32 v24, -v99, v32, v24
	v_fma_f32 v27, -v106, v39, v27
	ds_read_b128 v[56:59], v92 offset:12160
	v_fma_f32 v26, -v105, v38, v26
	v_fma_f32 v25, -v104, v37, v25
	v_fma_f32 v24, -v103, v36, v24
	s_waitcnt lgkmcnt(4)
	v_fma_f32 v27, -v110, v43, v27
	ds_read_b128 v[60:63], v92 offset:12176
	v_fma_f32 v26, -v109, v42, v26
	v_fma_f32 v25, -v108, v41, v25
	v_fma_f32 v24, -v107, v40, v24
	s_waitcnt lgkmcnt(4)
	v_fma_f32 v27, -v114, v47, v27
	ds_read_b128 v[64:67], v92 offset:12192
	v_fma_f32 v26, -v113, v46, v26
	v_fma_f32 v25, -v112, v45, v25
	v_fma_f32 v24, -v111, v44, v24
	s_waitcnt lgkmcnt(4)
	v_fma_f32 v27, -v118, v51, v27
	ds_read_b128 v[70:73], v92 offset:12208
	v_fma_f32 v26, -v117, v50, v26
	v_fma_f32 v25, -v116, v49, v25
	v_fma_f32 v24, -v115, v48, v24
	s_waitcnt lgkmcnt(4)
	v_fma_f32 v27, -v122, v55, v27
	v_fma_f32 v26, -v121, v54, v26
	v_fma_f32 v25, -v120, v53, v25
	v_fma_f32 v24, -v119, v52, v24
	s_waitcnt lgkmcnt(3)
	v_fma_f32 v27, -v126, v59, v27
	v_fma_f32 v26, -v125, v58, v26
	v_fma_f32 v25, -v124, v57, v25
	v_fma_f32 v24, -v123, v56, v24
	ds_read_b128 v[28:31], v92 offset:12288
	s_waitcnt lgkmcnt(3)
	v_fma_f32 v27, -v135, v63, v27
	v_fma_f32 v26, -v134, v62, v26
	v_fma_f32 v25, -v133, v61, v25
	v_fma_f32 v24, -v127, v60, v24
	ds_read_b128 v[32:35], v92 offset:12304
	s_waitcnt lgkmcnt(3)
	v_fma_f32 v27, -v139, v67, v27
	v_fma_f32 v26, -v138, v66, v26
	v_fma_f32 v25, -v137, v65, v25
	v_fma_f32 v24, -v136, v64, v24
	ds_read_b128 v[36:39], v92 offset:12320
	s_waitcnt lgkmcnt(3)
	v_fma_f32 v26, -v72, v142, v26
	v_fma_f32 v25, -v141, v71, v25
	v_fma_f32 v24, -v140, v70, v24
	ds_read_b128 v[40:43], v92 offset:12336
	v_add_f32_e32 v24, v25, v24
	v_add_f32_e32 v25, v27, v26
	ds_read_b128 v[44:47], v92 offset:12352
	v_add_f32_e32 v143, v25, v24
	s_waitcnt lgkmcnt(4)
	v_fma_f32 v24, -v93, v31, 0
	ds_read_b128 v[48:51], v92 offset:12368
	s_waitcnt lgkmcnt(4)
	v_fma_f32 v24, -v98, v35, v24
	ds_read_b128 v[52:55], v92 offset:12384
	s_waitcnt lgkmcnt(4)
	v_fma_f32 v24, -v102, v39, v24
	ds_read_b128 v[56:59], v92 offset:12400
	s_waitcnt lgkmcnt(4)
	v_fma_f32 v24, -v106, v43, v24
	ds_read_b128 v[60:63], v92 offset:12416
	s_waitcnt lgkmcnt(4)
	v_fma_f32 v24, -v110, v47, v24
	ds_read_b128 v[64:67], v92 offset:12432
	s_waitcnt lgkmcnt(4)
	v_fma_f32 v24, -v114, v51, v24
	ds_read_b128 v[68:71], v92 offset:12448
	v_add_u32_e32 v76, v74, v97
	s_waitcnt lgkmcnt(4)
	v_fma_f32 v24, -v118, v55, v24
	ds_read_b128 v[72:75], v92 offset:12464
	s_waitcnt lgkmcnt(4)
	v_fma_f32 v24, -v122, v59, v24
	s_waitcnt lgkmcnt(3)
	v_fma_f32 v24, -v126, v63, v24
	s_waitcnt lgkmcnt(2)
	v_fma_f32 v24, -v135, v67, v24
	s_waitcnt lgkmcnt(1)
	v_fma_f32 v24, -v139, v71, v24
	s_waitcnt lgkmcnt(0)
	v_fma_f32 v31, -v75, v143, v24
	v_fma_f32 v24, -v91, v30, 0
	v_fma_f32 v24, -v96, v34, v24
	v_fma_f32 v24, -v101, v38, v24
	v_fma_f32 v24, -v105, v42, v24
	v_fma_f32 v24, -v109, v46, v24
	v_fma_f32 v24, -v113, v50, v24
	v_fma_f32 v24, -v117, v54, v24
	v_fma_f32 v24, -v121, v58, v24
	v_fma_f32 v24, -v125, v62, v24
	v_fma_f32 v24, -v134, v66, v24
	v_fma_f32 v24, -v138, v70, v24
	v_fma_f32 v30, -v142, v74, v24
	v_fma_f32 v24, -v90, v29, 0
	v_fma_f32 v24, -v95, v33, v24
	v_fma_f32 v24, -v100, v37, v24
	v_fma_f32 v24, -v104, v41, v24
	v_fma_f32 v24, -v108, v45, v24
	v_fma_f32 v24, -v112, v49, v24
	v_fma_f32 v24, -v116, v53, v24
	v_fma_f32 v24, -v120, v57, v24
	v_fma_f32 v24, -v124, v61, v24
	v_fma_f32 v24, -v133, v65, v24
	v_fma_f32 v24, -v137, v69, v24
	v_fma_f32 v29, -v141, v73, v24
	ds_read_b128 v[24:27], v84 offset:192
	ds_read_u16 v33, v76
	v_mul_f32_e32 v28, v89, v28
	v_add_u32_e32 v80, v76, v97
	ds_read_b128 v[76:79], v92 offset:12736
	s_waitcnt lgkmcnt(1)
	v_lshlrev_b32_e32 v33, 16, v33
	v_fma_f32 v24, v24, v33, -v28
	v_fma_f32 v24, -v94, v32, v24
	v_fma_f32 v24, -v99, v36, v24
	v_fma_f32 v24, -v103, v40, v24
	v_fma_f32 v24, -v107, v44, v24
	v_fma_f32 v24, -v111, v48, v24
	v_fma_f32 v24, -v115, v52, v24
	v_fma_f32 v24, -v119, v56, v24
	v_fma_f32 v24, -v123, v60, v24
	v_fma_f32 v24, -v127, v64, v24
	v_fma_f32 v24, -v136, v68, v24
	v_fma_f32 v24, -v140, v72, v24
	v_add_f32_e32 v24, v29, v24
	v_add_f32_e32 v28, v30, v31
	v_add_f32_e32 v144, v28, v24
	ds_read_b128 v[28:31], v92 offset:12544
	ds_read_b128 v[32:35], v92 offset:12560
	ds_read_b128 v[36:39], v92 offset:12576
	ds_read_b128 v[40:43], v92 offset:12592
	ds_read_b128 v[44:47], v92 offset:12608
	s_waitcnt lgkmcnt(4)
	v_fma_f32 v29, -v90, v29, 0
	s_waitcnt lgkmcnt(3)
	v_fma_f32 v29, -v95, v33, v29
	ds_read_u16 v33, v80
	v_mul_f32_e32 v28, v89, v28
	v_fma_f32 v31, -v93, v31, 0
	ds_read_b128 v[48:51], v92 offset:12624
	v_fma_f32 v30, -v91, v30, 0
	s_waitcnt lgkmcnt(1)
	v_lshlrev_b32_e32 v33, 16, v33
	v_fma_f32 v25, v25, v33, -v28
	v_fma_f32 v31, -v98, v35, v31
	ds_read_b128 v[52:55], v92 offset:12640
	v_fma_f32 v30, -v96, v34, v30
	v_fma_f32 v25, -v94, v32, v25
	v_fma_f32 v31, -v102, v39, v31
	ds_read_b128 v[56:59], v92 offset:12656
	v_fma_f32 v30, -v101, v38, v30
	v_fma_f32 v29, -v100, v37, v29
	v_fma_f32 v25, -v99, v36, v25
	v_fma_f32 v31, -v106, v43, v31
	ds_read_b128 v[60:63], v92 offset:12672
	v_fma_f32 v30, -v105, v42, v30
	v_fma_f32 v29, -v104, v41, v29
	v_fma_f32 v25, -v103, v40, v25
	v_fma_f32 v31, -v110, v47, v31
	ds_read_b128 v[64:67], v92 offset:12688
	v_fma_f32 v30, -v109, v46, v30
	v_fma_f32 v29, -v108, v45, v29
	v_fma_f32 v25, -v107, v44, v25
	s_waitcnt lgkmcnt(4)
	v_fma_f32 v31, -v114, v51, v31
	ds_read_b128 v[68:71], v92 offset:12704
	v_fma_f32 v30, -v113, v50, v30
	v_fma_f32 v29, -v112, v49, v29
	v_fma_f32 v25, -v111, v48, v25
	s_waitcnt lgkmcnt(4)
	v_fma_f32 v31, -v118, v55, v31
	ds_read_b128 v[72:75], v92 offset:12720
	v_fma_f32 v30, -v117, v54, v30
	v_fma_f32 v29, -v116, v53, v29
	v_fma_f32 v25, -v115, v52, v25
	s_waitcnt lgkmcnt(4)
	v_fma_f32 v31, -v122, v59, v31
	v_fma_f32 v30, -v121, v58, v30
	v_fma_f32 v29, -v120, v57, v29
	v_fma_f32 v25, -v119, v56, v25
	s_waitcnt lgkmcnt(3)
	v_fma_f32 v31, -v126, v63, v31
	v_fma_f32 v30, -v125, v62, v30
	v_fma_f32 v29, -v124, v61, v29
	v_fma_f32 v25, -v123, v60, v25
	s_waitcnt lgkmcnt(2)
	v_fma_f32 v31, -v135, v67, v31
	v_fma_f32 v30, -v134, v66, v30
	v_fma_f32 v29, -v133, v65, v29
	v_fma_f32 v25, -v127, v64, v25
	s_waitcnt lgkmcnt(1)
	v_fma_f32 v31, -v139, v71, v31
	v_fma_f32 v30, -v138, v70, v30
	v_fma_f32 v29, -v137, v69, v29
	v_fma_f32 v25, -v136, v68, v25
	s_waitcnt lgkmcnt(0)
	v_fma_f32 v31, -v143, v75, v31
	v_fma_f32 v30, -v142, v74, v30
	v_fma_f32 v29, -v141, v73, v29
	v_fma_f32 v25, -v140, v72, v25
	v_fma_f32 v25, -v76, v144, v25
	v_add_u32_e32 v24, v80, v97
	v_add_f32_e32 v25, v29, v25
	v_add_f32_e32 v28, v30, v31
	v_add_f32_e32 v145, v28, v25
	v_add_u32_e32 v25, v24, v97
	ds_read_b128 v[28:31], v92 offset:12800
	ds_read_u16 v24, v24
	ds_read_b128 v[32:35], v92 offset:12816
	ds_read_b128 v[36:39], v92 offset:12832
	ds_read_b128 v[40:43], v92 offset:12848
	ds_read_b128 v[44:47], v92 offset:12864
	s_waitcnt lgkmcnt(4)
	v_lshlrev_b32_e32 v24, 16, v24
	v_mul_f32_e32 v28, v89, v28
	v_fma_f32 v31, -v93, v31, 0
	ds_read_b128 v[48:51], v92 offset:12880
	v_fma_f32 v30, -v91, v30, 0
	v_fma_f32 v29, -v90, v29, 0
	v_fma_f32 v24, v26, v24, -v28
	s_waitcnt lgkmcnt(4)
	v_fma_f32 v31, -v98, v35, v31
	ds_read_b128 v[52:55], v92 offset:12896
	v_fma_f32 v30, -v96, v34, v30
	v_fma_f32 v29, -v95, v33, v29
	v_fma_f32 v24, -v94, v32, v24
	s_waitcnt lgkmcnt(4)
	v_fma_f32 v31, -v102, v39, v31
	ds_read_b128 v[56:59], v92 offset:12912
	v_fma_f32 v30, -v101, v38, v30
	v_fma_f32 v29, -v100, v37, v29
	v_fma_f32 v24, -v99, v36, v24
	s_waitcnt lgkmcnt(4)
	v_fma_f32 v31, -v106, v43, v31
	ds_read_b128 v[60:63], v92 offset:12928
	v_fma_f32 v30, -v105, v42, v30
	v_fma_f32 v29, -v104, v41, v29
	v_fma_f32 v24, -v103, v40, v24
	s_waitcnt lgkmcnt(4)
	v_fma_f32 v31, -v110, v47, v31
	ds_read_b128 v[64:67], v92 offset:12944
	v_fma_f32 v30, -v109, v46, v30
	v_fma_f32 v29, -v108, v45, v29
	v_fma_f32 v24, -v107, v44, v24
	s_waitcnt lgkmcnt(4)
	v_fma_f32 v31, -v114, v51, v31
	ds_read_b128 v[68:71], v92 offset:12960
	v_fma_f32 v30, -v113, v50, v30
	v_fma_f32 v29, -v112, v49, v29
	v_fma_f32 v24, -v111, v48, v24
	s_waitcnt lgkmcnt(4)
	v_fma_f32 v31, -v118, v55, v31
	ds_read_b128 v[72:75], v92 offset:12976
	v_fma_f32 v30, -v117, v54, v30
	v_fma_f32 v29, -v116, v53, v29
	v_fma_f32 v24, -v115, v52, v24
	s_waitcnt lgkmcnt(4)
	v_fma_f32 v31, -v122, v59, v31
	ds_read_b128 v[76:79], v92 offset:12992
	v_fma_f32 v30, -v121, v58, v30
	v_fma_f32 v29, -v120, v57, v29
	v_fma_f32 v24, -v119, v56, v24
	s_waitcnt lgkmcnt(4)
	v_fma_f32 v31, -v126, v63, v31
	v_fma_f32 v30, -v125, v62, v30
	v_fma_f32 v29, -v124, v61, v29
	v_fma_f32 v24, -v123, v60, v24
	s_waitcnt lgkmcnt(3)
	v_fma_f32 v31, -v135, v67, v31
	v_fma_f32 v30, -v134, v66, v30
	v_fma_f32 v29, -v133, v65, v29
	v_fma_f32 v24, -v127, v64, v24
	s_waitcnt lgkmcnt(2)
	v_fma_f32 v31, -v139, v71, v31
	v_fma_f32 v30, -v138, v70, v30
	v_fma_f32 v29, -v137, v69, v29
	v_fma_f32 v24, -v136, v68, v24
	s_waitcnt lgkmcnt(1)
	v_fma_f32 v31, -v143, v75, v31
	v_fma_f32 v30, -v142, v74, v30
	v_fma_f32 v29, -v141, v73, v29
	v_fma_f32 v24, -v140, v72, v24
	s_waitcnt lgkmcnt(0)
	v_fma_f32 v29, -v77, v145, v29
	v_fma_f32 v24, -v144, v76, v24
	v_add_f32_e32 v24, v29, v24
	v_add_f32_e32 v26, v30, v31
	v_add_u32_e32 v79, v25, v97
	ds_read_b128 v[28:31], v92 offset:13056
	ds_read_u16 v25, v25
	ds_read_b128 v[32:35], v92 offset:13072
	ds_read_b128 v[36:39], v92 offset:13088
	ds_read_b128 v[40:43], v92 offset:13104
	ds_read_b128 v[44:47], v92 offset:13120
	s_waitcnt lgkmcnt(4)
	v_lshlrev_b32_e32 v25, 16, v25
	v_mul_f32_e32 v28, v89, v28
	v_add_f32_e32 v146, v26, v24
	v_fma_f32 v24, -v93, v31, 0
	ds_read_b128 v[48:51], v92 offset:13136
	v_fma_f32 v26, -v91, v30, 0
	v_fma_f32 v29, -v90, v29, 0
	v_fma_f32 v25, v27, v25, -v28
	s_waitcnt lgkmcnt(4)
	v_fma_f32 v24, -v98, v35, v24
	ds_read_b128 v[52:55], v92 offset:13152
	v_fma_f32 v26, -v96, v34, v26
	v_fma_f32 v29, -v95, v33, v29
	v_fma_f32 v25, -v94, v32, v25
	s_waitcnt lgkmcnt(4)
	v_fma_f32 v24, -v102, v39, v24
	ds_read_b128 v[56:59], v92 offset:13168
	v_fma_f32 v26, -v101, v38, v26
	v_fma_f32 v29, -v100, v37, v29
	v_fma_f32 v25, -v99, v36, v25
	s_waitcnt lgkmcnt(4)
	v_fma_f32 v24, -v106, v43, v24
	ds_read_b128 v[60:63], v92 offset:13184
	v_fma_f32 v26, -v105, v42, v26
	v_fma_f32 v29, -v104, v41, v29
	v_fma_f32 v25, -v103, v40, v25
	s_waitcnt lgkmcnt(4)
	v_fma_f32 v24, -v110, v47, v24
	ds_read_b128 v[64:67], v92 offset:13200
	v_fma_f32 v26, -v109, v46, v26
	v_fma_f32 v29, -v108, v45, v29
	v_fma_f32 v25, -v107, v44, v25
	s_waitcnt lgkmcnt(4)
	v_fma_f32 v24, -v114, v51, v24
	ds_read_b128 v[68:71], v92 offset:13216
	v_fma_f32 v26, -v113, v50, v26
	v_fma_f32 v29, -v112, v49, v29
	v_fma_f32 v25, -v111, v48, v25
	s_waitcnt lgkmcnt(4)
	v_fma_f32 v24, -v118, v55, v24
	ds_read_b128 v[72:75], v92 offset:13232
	v_fma_f32 v26, -v117, v54, v26
	v_fma_f32 v29, -v116, v53, v29
	v_fma_f32 v25, -v115, v52, v25
	s_waitcnt lgkmcnt(4)
	v_fma_f32 v24, -v122, v59, v24
	ds_read_b128 v[80:83], v92 offset:13248
	v_fma_f32 v26, -v121, v58, v26
	v_fma_f32 v29, -v120, v57, v29
	v_fma_f32 v25, -v119, v56, v25
	s_waitcnt lgkmcnt(4)
	v_fma_f32 v24, -v126, v63, v24
	v_fma_f32 v26, -v125, v62, v26
	v_fma_f32 v29, -v124, v61, v29
	v_fma_f32 v25, -v123, v60, v25
	s_waitcnt lgkmcnt(3)
	v_fma_f32 v24, -v135, v67, v24
	v_fma_f32 v26, -v134, v66, v26
	v_fma_f32 v29, -v133, v65, v29
	v_fma_f32 v25, -v127, v64, v25
	s_waitcnt lgkmcnt(2)
	v_fma_f32 v24, -v139, v71, v24
	v_fma_f32 v26, -v138, v70, v26
	v_fma_f32 v29, -v137, v69, v29
	v_fma_f32 v25, -v136, v68, v25
	s_waitcnt lgkmcnt(1)
	v_fma_f32 v24, -v143, v75, v24
	v_fma_f32 v26, -v142, v74, v26
	v_fma_f32 v29, -v141, v73, v29
	v_fma_f32 v25, -v140, v72, v25
	s_waitcnt lgkmcnt(0)
	v_fma_f32 v26, -v82, v146, v26
	v_fma_f32 v29, -v145, v81, v29
	v_fma_f32 v25, -v144, v80, v25
	v_add_f32_e32 v25, v29, v25
	v_add_f32_e32 v24, v24, v26
	v_add_f32_e32 v147, v24, v25
	ds_read_b128 v[24:27], v92 offset:13312
	ds_read_b128 v[28:31], v92 offset:13328
	ds_read_b128 v[32:35], v92 offset:13344
	ds_read_b128 v[36:39], v92 offset:13360
	ds_read_b128 v[40:43], v92 offset:13376
	s_waitcnt lgkmcnt(4)
	v_fma_f32 v27, -v93, v27, 0
	ds_read_b128 v[44:47], v92 offset:13392
	v_fma_f32 v26, -v91, v26, 0
	s_waitcnt lgkmcnt(4)
	v_fma_f32 v27, -v98, v31, v27
	ds_read_b128 v[48:51], v92 offset:13408
	v_fma_f32 v26, -v96, v30, v26
	s_waitcnt lgkmcnt(4)
	v_fma_f32 v27, -v102, v35, v27
	ds_read_b128 v[52:55], v92 offset:13424
	v_fma_f32 v26, -v101, v34, v26
	s_waitcnt lgkmcnt(4)
	v_fma_f32 v27, -v106, v39, v27
	ds_read_b128 v[56:59], v92 offset:13440
	v_fma_f32 v26, -v105, v38, v26
	s_waitcnt lgkmcnt(4)
	v_fma_f32 v27, -v110, v43, v27
	ds_read_b128 v[60:63], v92 offset:13456
	v_fma_f32 v26, -v109, v42, v26
	s_waitcnt lgkmcnt(4)
	v_fma_f32 v27, -v114, v47, v27
	ds_read_b128 v[64:67], v92 offset:13472
	v_fma_f32 v26, -v113, v46, v26
	s_waitcnt lgkmcnt(4)
	v_fma_f32 v27, -v118, v51, v27
	ds_read_b128 v[68:71], v92 offset:13488
	v_fma_f32 v26, -v117, v50, v26
	s_waitcnt lgkmcnt(4)
	v_fma_f32 v27, -v122, v55, v27
	ds_read_b128 v[72:75], v92 offset:13504
	v_fma_f32 v26, -v121, v54, v26
	s_waitcnt lgkmcnt(4)
	v_fma_f32 v27, -v126, v59, v27
	v_fma_f32 v26, -v125, v58, v26
	s_waitcnt lgkmcnt(3)
	v_fma_f32 v27, -v135, v63, v27
	v_fma_f32 v26, -v134, v62, v26
	s_waitcnt lgkmcnt(2)
	v_fma_f32 v27, -v139, v67, v27
	v_fma_f32 v26, -v138, v66, v26
	s_waitcnt lgkmcnt(1)
	v_fma_f32 v27, -v143, v71, v27
	v_fma_f32 v26, -v142, v70, v26
	v_fma_f32 v25, -v90, v25, 0
	s_waitcnt lgkmcnt(0)
	v_fma_f32 v27, -v75, v147, v27
	v_fma_f32 v26, -v146, v74, v26
	v_fma_f32 v25, -v95, v29, v25
	ds_read_b128 v[74:77], v84 offset:208
	ds_read_u16 v29, v79
	v_mul_f32_e32 v24, v89, v24
	v_fma_f32 v25, -v100, v33, v25
	v_fma_f32 v25, -v104, v37, v25
	v_fma_f32 v25, -v108, v41, v25
	s_waitcnt lgkmcnt(0)
	v_lshlrev_b32_e32 v29, 16, v29
	v_fma_f32 v24, v74, v29, -v24
	v_fma_f32 v24, -v94, v28, v24
	v_fma_f32 v24, -v99, v32, v24
	v_fma_f32 v24, -v103, v36, v24
	v_fma_f32 v24, -v107, v40, v24
	v_fma_f32 v25, -v112, v45, v25
	v_fma_f32 v24, -v111, v44, v24
	v_fma_f32 v25, -v116, v49, v25
	v_fma_f32 v24, -v115, v48, v24
	v_fma_f32 v25, -v120, v53, v25
	v_fma_f32 v24, -v119, v52, v24
	v_fma_f32 v25, -v124, v57, v25
	v_fma_f32 v24, -v123, v56, v24
	v_fma_f32 v25, -v133, v61, v25
	v_fma_f32 v24, -v127, v60, v24
	v_fma_f32 v25, -v137, v65, v25
	v_fma_f32 v24, -v136, v64, v24
	v_fma_f32 v25, -v141, v69, v25
	v_fma_f32 v24, -v140, v68, v24
	v_fma_f32 v25, -v145, v73, v25
	v_fma_f32 v24, -v144, v72, v24
	v_add_f32_e32 v24, v25, v24
	v_add_f32_e32 v25, v26, v27
	v_add_f32_e32 v148, v25, v24
	ds_read_b128 v[24:27], v92 offset:13568
	ds_read_b128 v[28:31], v92 offset:13584
	v_add_u32_e32 v78, v79, v97
	ds_read_b128 v[32:35], v92 offset:13600
	ds_read_b128 v[36:39], v92 offset:13616
	s_waitcnt lgkmcnt(3)
	v_fma_f32 v25, -v90, v25, 0
	s_waitcnt lgkmcnt(2)
	v_fma_f32 v25, -v95, v29, v25
	ds_read_u16 v29, v78
	ds_read_b128 v[40:43], v92 offset:13632
	v_mul_f32_e32 v24, v89, v24
	v_fma_f32 v27, -v93, v27, 0
	ds_read_b128 v[44:47], v92 offset:13648
	s_waitcnt lgkmcnt(2)
	v_lshlrev_b32_e32 v29, 16, v29
	v_fma_f32 v26, -v91, v26, 0
	v_fma_f32 v24, v75, v29, -v24
	v_fma_f32 v27, -v98, v31, v27
	ds_read_b128 v[48:51], v92 offset:13664
	v_fma_f32 v26, -v96, v30, v26
	v_fma_f32 v24, -v94, v28, v24
	v_fma_f32 v27, -v102, v35, v27
	ds_read_b128 v[52:55], v92 offset:13680
	v_fma_f32 v26, -v101, v34, v26
	v_fma_f32 v25, -v100, v33, v25
	v_fma_f32 v24, -v99, v32, v24
	v_fma_f32 v27, -v106, v39, v27
	ds_read_b128 v[56:59], v92 offset:13696
	v_fma_f32 v26, -v105, v38, v26
	v_fma_f32 v25, -v104, v37, v25
	v_fma_f32 v24, -v103, v36, v24
	s_waitcnt lgkmcnt(4)
	v_fma_f32 v27, -v110, v43, v27
	ds_read_b128 v[60:63], v92 offset:13712
	v_fma_f32 v26, -v109, v42, v26
	v_fma_f32 v25, -v108, v41, v25
	v_fma_f32 v24, -v107, v40, v24
	s_waitcnt lgkmcnt(4)
	v_fma_f32 v27, -v114, v47, v27
	ds_read_b128 v[64:67], v92 offset:13728
	v_fma_f32 v26, -v113, v46, v26
	v_fma_f32 v25, -v112, v45, v25
	v_fma_f32 v24, -v111, v44, v24
	s_waitcnt lgkmcnt(4)
	v_fma_f32 v27, -v118, v51, v27
	ds_read_b128 v[68:71], v92 offset:13744
	v_fma_f32 v26, -v117, v50, v26
	v_fma_f32 v25, -v116, v49, v25
	v_fma_f32 v24, -v115, v48, v24
	s_waitcnt lgkmcnt(4)
	v_fma_f32 v27, -v122, v55, v27
	ds_read_b128 v[80:83], v92 offset:13760
	ds_read_b128 v[150:153], v92 offset:13776
	v_fma_f32 v26, -v121, v54, v26
	v_fma_f32 v25, -v120, v53, v25
	v_fma_f32 v24, -v119, v52, v24
	s_waitcnt lgkmcnt(5)
	v_fma_f32 v27, -v126, v59, v27
	v_fma_f32 v26, -v125, v58, v26
	v_fma_f32 v25, -v124, v57, v25
	v_fma_f32 v24, -v123, v56, v24
	s_waitcnt lgkmcnt(4)
	v_fma_f32 v27, -v135, v63, v27
	v_fma_f32 v26, -v134, v62, v26
	v_fma_f32 v25, -v133, v61, v25
	v_fma_f32 v24, -v127, v60, v24
	s_waitcnt lgkmcnt(3)
	v_fma_f32 v27, -v139, v67, v27
	v_fma_f32 v26, -v138, v66, v26
	v_fma_f32 v25, -v137, v65, v25
	v_fma_f32 v24, -v136, v64, v24
	s_waitcnt lgkmcnt(2)
	v_fma_f32 v27, -v143, v71, v27
	v_fma_f32 v26, -v142, v70, v26
	v_fma_f32 v25, -v141, v69, v25
	v_fma_f32 v24, -v140, v68, v24
	s_waitcnt lgkmcnt(1)
	v_fma_f32 v27, -v147, v83, v27
	v_fma_f32 v26, -v146, v82, v26
	v_fma_f32 v25, -v145, v81, v25
	v_fma_f32 v24, -v144, v80, v24
	s_waitcnt lgkmcnt(0)
	v_fma_f32 v24, -v150, v148, v24
	v_add_f32_e32 v24, v25, v24
	v_add_f32_e32 v25, v26, v27
	v_add_f32_e32 v149, v25, v24
	ds_read_b128 v[24:27], v92 offset:13824
	ds_read_b128 v[28:31], v92 offset:13840
	v_add_u32_e32 v85, v78, v97
	ds_read_b128 v[32:35], v92 offset:13856
	ds_read_b128 v[36:39], v92 offset:13872
	s_waitcnt lgkmcnt(3)
	v_fma_f32 v25, -v90, v25, 0
	s_waitcnt lgkmcnt(2)
	v_fma_f32 v25, -v95, v29, v25
	ds_read_u16 v29, v85
	ds_read_b128 v[40:43], v92 offset:13888
	v_mul_f32_e32 v24, v89, v24
	v_fma_f32 v27, -v93, v27, 0
	ds_read_b128 v[44:47], v92 offset:13904
	s_waitcnt lgkmcnt(2)
	v_lshlrev_b32_e32 v29, 16, v29
	v_fma_f32 v26, -v91, v26, 0
	v_fma_f32 v24, v76, v29, -v24
	v_fma_f32 v27, -v98, v31, v27
	ds_read_b128 v[48:51], v92 offset:13920
	v_fma_f32 v26, -v96, v30, v26
	v_fma_f32 v24, -v94, v28, v24
	v_fma_f32 v27, -v102, v35, v27
	ds_read_b128 v[52:55], v92 offset:13936
	v_fma_f32 v26, -v101, v34, v26
	v_fma_f32 v25, -v100, v33, v25
	v_fma_f32 v24, -v99, v32, v24
	v_fma_f32 v27, -v106, v39, v27
	ds_read_b128 v[56:59], v92 offset:13952
	v_fma_f32 v26, -v105, v38, v26
	v_fma_f32 v25, -v104, v37, v25
	v_fma_f32 v24, -v103, v36, v24
	s_waitcnt lgkmcnt(4)
	v_fma_f32 v27, -v110, v43, v27
	ds_read_b128 v[60:63], v92 offset:13968
	v_fma_f32 v26, -v109, v42, v26
	v_fma_f32 v25, -v108, v41, v25
	v_fma_f32 v24, -v107, v40, v24
	s_waitcnt lgkmcnt(4)
	v_fma_f32 v27, -v114, v47, v27
	ds_read_b128 v[64:67], v92 offset:13984
	v_fma_f32 v26, -v113, v46, v26
	v_fma_f32 v25, -v112, v45, v25
	v_fma_f32 v24, -v111, v44, v24
	s_waitcnt lgkmcnt(4)
	v_fma_f32 v27, -v118, v51, v27
	ds_read_b128 v[68:71], v92 offset:14000
	v_fma_f32 v26, -v117, v50, v26
	v_fma_f32 v25, -v116, v49, v25
	v_fma_f32 v24, -v115, v48, v24
	s_waitcnt lgkmcnt(4)
	v_fma_f32 v27, -v122, v55, v27
	ds_read_b128 v[72:75], v92 offset:14016
	v_fma_f32 v26, -v121, v54, v26
	v_fma_f32 v25, -v120, v53, v25
	v_fma_f32 v24, -v119, v52, v24
	s_waitcnt lgkmcnt(4)
	v_fma_f32 v27, -v126, v59, v27
	ds_read_b128 v[78:81], v92 offset:14032
	v_fma_f32 v26, -v125, v58, v26
	v_fma_f32 v25, -v124, v57, v25
	v_fma_f32 v24, -v123, v56, v24
	s_waitcnt lgkmcnt(4)
	v_fma_f32 v27, -v135, v63, v27
	v_fma_f32 v26, -v134, v62, v26
	v_fma_f32 v25, -v133, v61, v25
	v_fma_f32 v24, -v127, v60, v24
	s_waitcnt lgkmcnt(3)
	v_fma_f32 v27, -v139, v67, v27
	v_fma_f32 v26, -v138, v66, v26
	v_fma_f32 v25, -v137, v65, v25
	v_fma_f32 v24, -v136, v64, v24
	s_waitcnt lgkmcnt(2)
	v_fma_f32 v27, -v143, v71, v27
	v_fma_f32 v26, -v142, v70, v26
	v_fma_f32 v25, -v141, v69, v25
	v_fma_f32 v24, -v140, v68, v24
	s_waitcnt lgkmcnt(1)
	v_fma_f32 v27, -v147, v75, v27
	v_fma_f32 v26, -v146, v74, v26
	v_fma_f32 v25, -v145, v73, v25
	v_fma_f32 v24, -v144, v72, v24
	s_waitcnt lgkmcnt(0)
	v_fma_f32 v25, -v79, v149, v25
	v_fma_f32 v24, -v148, v78, v24
	v_add_f32_e32 v24, v25, v24
	v_add_f32_e32 v25, v26, v27
	v_add_f32_e32 v150, v25, v24
	ds_read_b128 v[24:27], v92 offset:14080
	ds_read_b128 v[28:31], v92 offset:14096
	v_add_u32_e32 v82, v85, v97
	ds_read_b128 v[32:35], v92 offset:14112
	ds_read_b128 v[36:39], v92 offset:14128
	s_waitcnt lgkmcnt(3)
	v_fma_f32 v25, -v90, v25, 0
	s_waitcnt lgkmcnt(2)
	v_fma_f32 v25, -v95, v29, v25
	ds_read_u16 v29, v82
	ds_read_b128 v[40:43], v92 offset:14144
	v_mul_f32_e32 v24, v89, v24
	v_fma_f32 v27, -v93, v27, 0
	ds_read_b128 v[44:47], v92 offset:14160
	s_waitcnt lgkmcnt(2)
	v_lshlrev_b32_e32 v29, 16, v29
	v_fma_f32 v26, -v91, v26, 0
	v_fma_f32 v24, v77, v29, -v24
	v_fma_f32 v27, -v98, v31, v27
	ds_read_b128 v[48:51], v92 offset:14176
	v_fma_f32 v26, -v96, v30, v26
	v_fma_f32 v24, -v94, v28, v24
	v_fma_f32 v27, -v102, v35, v27
	ds_read_b128 v[52:55], v92 offset:14192
	v_fma_f32 v26, -v101, v34, v26
	v_fma_f32 v25, -v100, v33, v25
	v_fma_f32 v24, -v99, v32, v24
	v_fma_f32 v27, -v106, v39, v27
	ds_read_b128 v[56:59], v92 offset:14208
	v_fma_f32 v26, -v105, v38, v26
	v_fma_f32 v25, -v104, v37, v25
	v_fma_f32 v24, -v103, v36, v24
	s_waitcnt lgkmcnt(4)
	v_fma_f32 v27, -v110, v43, v27
	ds_read_b128 v[60:63], v92 offset:14224
	v_fma_f32 v26, -v109, v42, v26
	v_fma_f32 v25, -v108, v41, v25
	v_fma_f32 v24, -v107, v40, v24
	s_waitcnt lgkmcnt(4)
	v_fma_f32 v27, -v114, v47, v27
	ds_read_b128 v[64:67], v92 offset:14240
	v_fma_f32 v26, -v113, v46, v26
	v_fma_f32 v25, -v112, v45, v25
	v_fma_f32 v24, -v111, v44, v24
	s_waitcnt lgkmcnt(4)
	v_fma_f32 v27, -v118, v51, v27
	ds_read_b128 v[68:71], v92 offset:14256
	v_fma_f32 v26, -v117, v50, v26
	v_fma_f32 v25, -v116, v49, v25
	v_fma_f32 v24, -v115, v48, v24
	s_waitcnt lgkmcnt(4)
	v_fma_f32 v27, -v122, v55, v27
	ds_read_b128 v[72:75], v92 offset:14272
	v_fma_f32 v26, -v121, v54, v26
	v_fma_f32 v25, -v120, v53, v25
	v_fma_f32 v24, -v119, v52, v24
	s_waitcnt lgkmcnt(4)
	v_fma_f32 v27, -v126, v59, v27
	ds_read_b128 v[78:81], v92 offset:14288
	v_fma_f32 v26, -v125, v58, v26
	v_fma_f32 v25, -v124, v57, v25
	v_fma_f32 v24, -v123, v56, v24
	s_waitcnt lgkmcnt(4)
	v_fma_f32 v27, -v135, v63, v27
	v_fma_f32 v26, -v134, v62, v26
	v_fma_f32 v25, -v133, v61, v25
	v_fma_f32 v24, -v127, v60, v24
	s_waitcnt lgkmcnt(3)
	v_fma_f32 v27, -v139, v67, v27
	v_fma_f32 v26, -v138, v66, v26
	v_fma_f32 v25, -v137, v65, v25
	v_fma_f32 v24, -v136, v64, v24
	ds_read_b128 v[28:31], v92 offset:14336
	s_waitcnt lgkmcnt(3)
	v_fma_f32 v27, -v143, v71, v27
	v_fma_f32 v26, -v142, v70, v26
	v_fma_f32 v25, -v141, v69, v25
	v_fma_f32 v24, -v140, v68, v24
	ds_read_b128 v[32:35], v92 offset:14352
	s_waitcnt lgkmcnt(3)
	v_fma_f32 v27, -v147, v75, v27
	v_fma_f32 v26, -v146, v74, v26
	v_fma_f32 v25, -v145, v73, v25
	v_fma_f32 v24, -v144, v72, v24
	ds_read_b128 v[36:39], v92 offset:14368
	s_waitcnt lgkmcnt(3)
	v_fma_f32 v26, -v80, v150, v26
	v_fma_f32 v25, -v149, v79, v25
	v_fma_f32 v24, -v148, v78, v24
	ds_read_b128 v[40:43], v92 offset:14384
	v_add_f32_e32 v24, v25, v24
	v_add_f32_e32 v25, v27, v26
	ds_read_b128 v[44:47], v92 offset:14400
	v_add_f32_e32 v151, v25, v24
	s_waitcnt lgkmcnt(4)
	v_fma_f32 v24, -v93, v31, 0
	ds_read_b128 v[48:51], v92 offset:14416
	s_waitcnt lgkmcnt(4)
	v_fma_f32 v24, -v98, v35, v24
	ds_read_b128 v[52:55], v92 offset:14432
	s_waitcnt lgkmcnt(4)
	v_fma_f32 v24, -v102, v39, v24
	ds_read_b128 v[56:59], v92 offset:14448
	s_waitcnt lgkmcnt(4)
	v_fma_f32 v24, -v106, v43, v24
	ds_read_b128 v[60:63], v92 offset:14464
	s_waitcnt lgkmcnt(4)
	v_fma_f32 v24, -v110, v47, v24
	ds_read_b128 v[64:67], v92 offset:14480
	s_waitcnt lgkmcnt(4)
	v_fma_f32 v24, -v114, v51, v24
	ds_read_b128 v[68:71], v92 offset:14496
	s_waitcnt lgkmcnt(4)
	v_fma_f32 v24, -v118, v55, v24
	ds_read_b128 v[72:75], v92 offset:14512
	s_waitcnt lgkmcnt(4)
	v_fma_f32 v24, -v122, v59, v24
	ds_read_b128 v[76:79], v92 offset:14528
	v_add_u32_e32 v85, v82, v97
	s_waitcnt lgkmcnt(4)
	v_fma_f32 v24, -v126, v63, v24
	ds_read_b128 v[80:83], v92 offset:14544
	s_waitcnt lgkmcnt(4)
	v_fma_f32 v24, -v135, v67, v24
	s_waitcnt lgkmcnt(3)
	v_fma_f32 v24, -v139, v71, v24
	s_waitcnt lgkmcnt(2)
	v_fma_f32 v24, -v143, v75, v24
	s_waitcnt lgkmcnt(1)
	v_fma_f32 v24, -v147, v79, v24
	s_waitcnt lgkmcnt(0)
	v_fma_f32 v31, -v83, v151, v24
	v_fma_f32 v24, -v91, v30, 0
	v_fma_f32 v24, -v96, v34, v24
	v_fma_f32 v24, -v101, v38, v24
	v_fma_f32 v24, -v105, v42, v24
	v_fma_f32 v24, -v109, v46, v24
	v_fma_f32 v24, -v113, v50, v24
	v_fma_f32 v24, -v117, v54, v24
	v_fma_f32 v24, -v121, v58, v24
	v_fma_f32 v24, -v125, v62, v24
	v_fma_f32 v24, -v134, v66, v24
	v_fma_f32 v24, -v138, v70, v24
	v_fma_f32 v24, -v142, v74, v24
	v_fma_f32 v24, -v146, v78, v24
	v_fma_f32 v30, -v150, v82, v24
	v_fma_f32 v24, -v90, v29, 0
	v_fma_f32 v24, -v95, v33, v24
	v_fma_f32 v24, -v100, v37, v24
	v_fma_f32 v24, -v104, v41, v24
	v_fma_f32 v24, -v108, v45, v24
	v_fma_f32 v24, -v112, v49, v24
	v_fma_f32 v24, -v116, v53, v24
	v_fma_f32 v24, -v120, v57, v24
	v_fma_f32 v24, -v124, v61, v24
	v_fma_f32 v24, -v133, v65, v24
	v_fma_f32 v24, -v137, v69, v24
	v_fma_f32 v24, -v141, v73, v24
	v_fma_f32 v24, -v145, v77, v24
	v_fma_f32 v29, -v149, v81, v24
	ds_read_b128 v[24:27], v84 offset:224
	ds_read_u16 v33, v85
	v_mul_f32_e32 v28, v89, v28
	v_add_u32_e32 v153, v85, v97
	ds_read_b128 v[154:157], v92 offset:14816
	ds_read_b128 v[158:161], v92 offset:15328
	s_waitcnt lgkmcnt(2)
	v_lshlrev_b32_e32 v33, 16, v33
	v_fma_f32 v24, v24, v33, -v28
	v_fma_f32 v24, -v94, v32, v24
	v_fma_f32 v24, -v99, v36, v24
	v_fma_f32 v24, -v103, v40, v24
	v_fma_f32 v24, -v107, v44, v24
	v_fma_f32 v24, -v111, v48, v24
	v_fma_f32 v24, -v115, v52, v24
	v_fma_f32 v24, -v119, v56, v24
	v_fma_f32 v24, -v123, v60, v24
	v_fma_f32 v24, -v127, v64, v24
	v_fma_f32 v24, -v136, v68, v24
	v_fma_f32 v24, -v140, v72, v24
	v_fma_f32 v24, -v144, v76, v24
	v_fma_f32 v24, -v148, v80, v24
	v_add_f32_e32 v24, v29, v24
	v_add_f32_e32 v28, v30, v31
	v_add_f32_e32 v152, v28, v24
	ds_read_b128 v[28:31], v92 offset:14592
	ds_read_b128 v[32:35], v92 offset:14608
	ds_read_b128 v[36:39], v92 offset:14624
	ds_read_b128 v[40:43], v92 offset:14640
	ds_read_b128 v[44:47], v92 offset:14656
	s_waitcnt lgkmcnt(4)
	v_fma_f32 v29, -v90, v29, 0
	s_waitcnt lgkmcnt(3)
	v_fma_f32 v29, -v95, v33, v29
	ds_read_u16 v33, v153
	v_mul_f32_e32 v28, v89, v28
	v_fma_f32 v31, -v93, v31, 0
	ds_read_b128 v[48:51], v92 offset:14672
	v_fma_f32 v30, -v91, v30, 0
	s_waitcnt lgkmcnt(1)
	v_lshlrev_b32_e32 v33, 16, v33
	v_fma_f32 v25, v25, v33, -v28
	v_fma_f32 v31, -v98, v35, v31
	ds_read_b128 v[52:55], v92 offset:14688
	v_fma_f32 v30, -v96, v34, v30
	v_fma_f32 v25, -v94, v32, v25
	v_fma_f32 v31, -v102, v39, v31
	ds_read_b128 v[56:59], v92 offset:14704
	v_fma_f32 v30, -v101, v38, v30
	v_fma_f32 v29, -v100, v37, v29
	v_fma_f32 v25, -v99, v36, v25
	v_fma_f32 v31, -v106, v43, v31
	ds_read_b128 v[60:63], v92 offset:14720
	v_fma_f32 v30, -v105, v42, v30
	v_fma_f32 v29, -v104, v41, v29
	v_fma_f32 v25, -v103, v40, v25
	v_fma_f32 v31, -v110, v47, v31
	ds_read_b128 v[64:67], v92 offset:14736
	v_fma_f32 v30, -v109, v46, v30
	v_fma_f32 v29, -v108, v45, v29
	v_fma_f32 v25, -v107, v44, v25
	s_waitcnt lgkmcnt(4)
	v_fma_f32 v31, -v114, v51, v31
	ds_read_b128 v[68:71], v92 offset:14752
	v_fma_f32 v30, -v113, v50, v30
	v_fma_f32 v29, -v112, v49, v29
	v_fma_f32 v25, -v111, v48, v25
	s_waitcnt lgkmcnt(4)
	v_fma_f32 v31, -v118, v55, v31
	ds_read_b128 v[72:75], v92 offset:14768
	v_fma_f32 v30, -v117, v54, v30
	v_fma_f32 v29, -v116, v53, v29
	v_fma_f32 v25, -v115, v52, v25
	s_waitcnt lgkmcnt(4)
	v_fma_f32 v31, -v122, v59, v31
	ds_read_b128 v[76:79], v92 offset:14784
	v_fma_f32 v30, -v121, v58, v30
	v_fma_f32 v29, -v120, v57, v29
	v_fma_f32 v25, -v119, v56, v25
	s_waitcnt lgkmcnt(4)
	v_fma_f32 v31, -v126, v63, v31
	ds_read_b128 v[80:83], v92 offset:14800
	v_fma_f32 v30, -v125, v62, v30
	v_fma_f32 v29, -v124, v61, v29
	v_fma_f32 v25, -v123, v60, v25
	s_waitcnt lgkmcnt(4)
	v_fma_f32 v31, -v135, v67, v31
	v_fma_f32 v30, -v134, v66, v30
	v_fma_f32 v29, -v133, v65, v29
	v_fma_f32 v25, -v127, v64, v25
	s_waitcnt lgkmcnt(3)
	v_fma_f32 v31, -v139, v71, v31
	v_fma_f32 v30, -v138, v70, v30
	v_fma_f32 v29, -v137, v69, v29
	v_fma_f32 v25, -v136, v68, v25
	s_waitcnt lgkmcnt(2)
	v_fma_f32 v31, -v143, v75, v31
	v_fma_f32 v30, -v142, v74, v30
	v_fma_f32 v29, -v141, v73, v29
	v_fma_f32 v25, -v140, v72, v25
	s_waitcnt lgkmcnt(1)
	v_fma_f32 v31, -v147, v79, v31
	v_fma_f32 v30, -v146, v78, v30
	v_fma_f32 v29, -v145, v77, v29
	v_fma_f32 v25, -v144, v76, v25
	s_waitcnt lgkmcnt(0)
	v_fma_f32 v31, -v151, v83, v31
	v_fma_f32 v30, -v150, v82, v30
	v_fma_f32 v29, -v149, v81, v29
	v_fma_f32 v25, -v148, v80, v25
	v_fma_f32 v25, -v154, v152, v25
	v_add_u32_e32 v24, v153, v97
	v_add_f32_e32 v25, v29, v25
	v_add_f32_e32 v28, v30, v31
	v_add_f32_e32 v153, v28, v25
	v_add_u32_e32 v25, v24, v97
	ds_read_b128 v[28:31], v92 offset:14848
	ds_read_u16 v24, v24
	ds_read_b128 v[32:35], v92 offset:14864
	ds_read_b128 v[36:39], v92 offset:14880
	ds_read_b128 v[40:43], v92 offset:14896
	ds_read_b128 v[44:47], v92 offset:14912
	s_waitcnt lgkmcnt(4)
	v_lshlrev_b32_e32 v24, 16, v24
	v_mul_f32_e32 v28, v89, v28
	v_fma_f32 v31, -v93, v31, 0
	ds_read_b128 v[48:51], v92 offset:14928
	v_fma_f32 v30, -v91, v30, 0
	v_fma_f32 v29, -v90, v29, 0
	v_fma_f32 v24, v26, v24, -v28
	s_waitcnt lgkmcnt(4)
	v_fma_f32 v31, -v98, v35, v31
	ds_read_b128 v[52:55], v92 offset:14944
	v_fma_f32 v30, -v96, v34, v30
	v_fma_f32 v29, -v95, v33, v29
	v_fma_f32 v24, -v94, v32, v24
	s_waitcnt lgkmcnt(4)
	v_fma_f32 v31, -v102, v39, v31
	ds_read_b128 v[56:59], v92 offset:14960
	v_fma_f32 v30, -v101, v38, v30
	v_fma_f32 v29, -v100, v37, v29
	v_fma_f32 v24, -v99, v36, v24
	s_waitcnt lgkmcnt(4)
	v_fma_f32 v31, -v106, v43, v31
	ds_read_b128 v[60:63], v92 offset:14976
	v_fma_f32 v30, -v105, v42, v30
	v_fma_f32 v29, -v104, v41, v29
	v_fma_f32 v24, -v103, v40, v24
	s_waitcnt lgkmcnt(4)
	v_fma_f32 v31, -v110, v47, v31
	ds_read_b128 v[64:67], v92 offset:14992
	v_fma_f32 v30, -v109, v46, v30
	v_fma_f32 v29, -v108, v45, v29
	v_fma_f32 v24, -v107, v44, v24
	s_waitcnt lgkmcnt(4)
	v_fma_f32 v31, -v114, v51, v31
	ds_read_b128 v[68:71], v92 offset:15008
	v_fma_f32 v30, -v113, v50, v30
	v_fma_f32 v29, -v112, v49, v29
	v_fma_f32 v24, -v111, v48, v24
	s_waitcnt lgkmcnt(4)
	v_fma_f32 v31, -v118, v55, v31
	ds_read_b128 v[72:75], v92 offset:15024
	v_fma_f32 v30, -v117, v54, v30
	v_fma_f32 v29, -v116, v53, v29
	v_fma_f32 v24, -v115, v52, v24
	s_waitcnt lgkmcnt(4)
	v_fma_f32 v31, -v122, v59, v31
	ds_read_b128 v[76:79], v92 offset:15040
	v_fma_f32 v30, -v121, v58, v30
	v_fma_f32 v29, -v120, v57, v29
	v_fma_f32 v24, -v119, v56, v24
	s_waitcnt lgkmcnt(4)
	v_fma_f32 v31, -v126, v63, v31
	ds_read_b128 v[80:83], v92 offset:15056
	v_fma_f32 v30, -v125, v62, v30
	v_fma_f32 v29, -v124, v61, v29
	v_fma_f32 v24, -v123, v60, v24
	s_waitcnt lgkmcnt(4)
	v_fma_f32 v31, -v135, v67, v31
	ds_read_b128 v[154:157], v92 offset:15072
	v_fma_f32 v30, -v134, v66, v30
	v_fma_f32 v29, -v133, v65, v29
	v_fma_f32 v24, -v127, v64, v24
	s_waitcnt lgkmcnt(4)
	v_fma_f32 v31, -v139, v71, v31
	v_fma_f32 v30, -v138, v70, v30
	v_fma_f32 v29, -v137, v69, v29
	v_fma_f32 v24, -v136, v68, v24
	s_waitcnt lgkmcnt(3)
	v_fma_f32 v31, -v143, v75, v31
	v_fma_f32 v30, -v142, v74, v30
	v_fma_f32 v29, -v141, v73, v29
	v_fma_f32 v24, -v140, v72, v24
	s_waitcnt lgkmcnt(2)
	v_fma_f32 v31, -v147, v79, v31
	v_fma_f32 v30, -v146, v78, v30
	v_fma_f32 v29, -v145, v77, v29
	v_fma_f32 v24, -v144, v76, v24
	s_waitcnt lgkmcnt(1)
	v_fma_f32 v31, -v151, v83, v31
	v_fma_f32 v30, -v150, v82, v30
	v_fma_f32 v29, -v149, v81, v29
	v_fma_f32 v24, -v148, v80, v24
	s_waitcnt lgkmcnt(0)
	v_fma_f32 v29, -v155, v153, v29
	v_fma_f32 v24, -v152, v154, v24
	v_add_f32_e32 v24, v29, v24
	v_add_f32_e32 v26, v30, v31
	v_add_u32_e32 v157, v25, v97
	ds_read_b128 v[28:31], v92 offset:15104
	ds_read_u16 v25, v25
	ds_read_b128 v[32:35], v92 offset:15120
	ds_read_b128 v[36:39], v92 offset:15136
	ds_read_b128 v[40:43], v92 offset:15152
	ds_read_b128 v[44:47], v92 offset:15168
	s_waitcnt lgkmcnt(4)
	v_lshlrev_b32_e32 v25, 16, v25
	v_mul_f32_e32 v28, v89, v28
	v_add_f32_e32 v154, v26, v24
	v_fma_f32 v24, -v93, v31, 0
	ds_read_b128 v[48:51], v92 offset:15184
	v_fma_f32 v26, -v91, v30, 0
	v_fma_f32 v29, -v90, v29, 0
	v_fma_f32 v25, v27, v25, -v28
	s_waitcnt lgkmcnt(4)
	v_fma_f32 v24, -v98, v35, v24
	ds_read_b128 v[52:55], v92 offset:15200
	v_fma_f32 v26, -v96, v34, v26
	v_fma_f32 v29, -v95, v33, v29
	v_fma_f32 v25, -v94, v32, v25
	s_waitcnt lgkmcnt(4)
	v_fma_f32 v24, -v102, v39, v24
	ds_read_b128 v[56:59], v92 offset:15216
	v_fma_f32 v26, -v101, v38, v26
	v_fma_f32 v29, -v100, v37, v29
	v_fma_f32 v25, -v99, v36, v25
	s_waitcnt lgkmcnt(4)
	v_fma_f32 v24, -v106, v43, v24
	ds_read_b128 v[60:63], v92 offset:15232
	v_fma_f32 v26, -v105, v42, v26
	v_fma_f32 v29, -v104, v41, v29
	v_fma_f32 v25, -v103, v40, v25
	s_waitcnt lgkmcnt(4)
	v_fma_f32 v24, -v110, v47, v24
	ds_read_b128 v[64:67], v92 offset:15248
	v_fma_f32 v26, -v109, v46, v26
	v_fma_f32 v29, -v108, v45, v29
	v_fma_f32 v25, -v107, v44, v25
	s_waitcnt lgkmcnt(4)
	v_fma_f32 v24, -v114, v51, v24
	ds_read_b128 v[68:71], v92 offset:15264
	v_fma_f32 v26, -v113, v50, v26
	v_fma_f32 v29, -v112, v49, v29
	v_fma_f32 v25, -v111, v48, v25
	s_waitcnt lgkmcnt(4)
	v_fma_f32 v24, -v118, v55, v24
	ds_read_b128 v[72:75], v92 offset:15280
	v_fma_f32 v26, -v117, v54, v26
	v_fma_f32 v29, -v116, v53, v29
	v_fma_f32 v25, -v115, v52, v25
	s_waitcnt lgkmcnt(4)
	v_fma_f32 v24, -v122, v59, v24
	ds_read_b128 v[76:79], v92 offset:15296
	v_fma_f32 v26, -v121, v58, v26
	v_fma_f32 v29, -v120, v57, v29
	v_fma_f32 v25, -v119, v56, v25
	s_waitcnt lgkmcnt(4)
	v_fma_f32 v24, -v126, v63, v24
	ds_read_b128 v[80:83], v92 offset:15312
	v_fma_f32 v26, -v125, v62, v26
	v_fma_f32 v29, -v124, v61, v29
	v_fma_f32 v25, -v123, v60, v25
	s_waitcnt lgkmcnt(4)
	v_fma_f32 v24, -v135, v67, v24
	v_fma_f32 v26, -v134, v66, v26
	v_fma_f32 v29, -v133, v65, v29
	v_fma_f32 v25, -v127, v64, v25
	s_waitcnt lgkmcnt(3)
	v_fma_f32 v24, -v139, v71, v24
	v_fma_f32 v26, -v138, v70, v26
	v_fma_f32 v29, -v137, v69, v29
	v_fma_f32 v25, -v136, v68, v25
	s_waitcnt lgkmcnt(2)
	v_fma_f32 v24, -v143, v75, v24
	v_fma_f32 v26, -v142, v74, v26
	v_fma_f32 v29, -v141, v73, v29
	v_fma_f32 v25, -v140, v72, v25
	s_waitcnt lgkmcnt(1)
	v_fma_f32 v24, -v147, v79, v24
	v_fma_f32 v26, -v146, v78, v26
	v_fma_f32 v29, -v145, v77, v29
	v_fma_f32 v25, -v144, v76, v25
	s_waitcnt lgkmcnt(0)
	v_fma_f32 v24, -v151, v83, v24
	v_fma_f32 v26, -v150, v82, v26
	v_fma_f32 v29, -v149, v81, v29
	v_fma_f32 v25, -v148, v80, v25
	v_fma_f32 v26, -v160, v154, v26
	v_fma_f32 v29, -v153, v159, v29
	v_fma_f32 v25, -v152, v158, v25
	v_add_f32_e32 v25, v29, v25
	v_add_f32_e32 v24, v24, v26
	v_add_f32_e32 v155, v24, v25
	ds_read_b128 v[24:27], v92 offset:15360
	ds_read_b128 v[28:31], v92 offset:15376
	ds_read_b128 v[32:35], v92 offset:15392
	ds_read_b128 v[36:39], v92 offset:15408
	ds_read_b128 v[40:43], v92 offset:15424
	s_waitcnt lgkmcnt(4)
	v_fma_f32 v27, -v93, v27, 0
	ds_read_b128 v[44:47], v92 offset:15440
	v_fma_f32 v26, -v91, v26, 0
	s_waitcnt lgkmcnt(4)
	v_fma_f32 v27, -v98, v31, v27
	ds_read_b128 v[48:51], v92 offset:15456
	v_fma_f32 v26, -v96, v30, v26
	s_waitcnt lgkmcnt(4)
	v_fma_f32 v27, -v102, v35, v27
	ds_read_b128 v[52:55], v92 offset:15472
	v_fma_f32 v26, -v101, v34, v26
	s_waitcnt lgkmcnt(4)
	v_fma_f32 v27, -v106, v39, v27
	ds_read_b128 v[56:59], v92 offset:15488
	v_fma_f32 v26, -v105, v38, v26
	s_waitcnt lgkmcnt(4)
	v_fma_f32 v27, -v110, v43, v27
	ds_read_b128 v[60:63], v92 offset:15504
	v_fma_f32 v26, -v109, v42, v26
	s_waitcnt lgkmcnt(4)
	v_fma_f32 v27, -v114, v47, v27
	ds_read_b128 v[64:67], v92 offset:15520
	v_fma_f32 v26, -v113, v46, v26
	s_waitcnt lgkmcnt(4)
	v_fma_f32 v27, -v118, v51, v27
	ds_read_b128 v[68:71], v92 offset:15536
	v_fma_f32 v26, -v117, v50, v26
	s_waitcnt lgkmcnt(4)
	v_fma_f32 v27, -v122, v55, v27
	ds_read_b128 v[72:75], v92 offset:15552
	v_fma_f32 v26, -v121, v54, v26
	s_waitcnt lgkmcnt(4)
	v_fma_f32 v27, -v126, v59, v27
	ds_read_b128 v[76:79], v92 offset:15568
	v_fma_f32 v26, -v125, v58, v26
	s_waitcnt lgkmcnt(4)
	v_fma_f32 v27, -v135, v63, v27
	ds_read_b128 v[80:83], v92 offset:15584
	v_fma_f32 v26, -v134, v62, v26
	s_waitcnt lgkmcnt(4)
	v_fma_f32 v27, -v139, v67, v27
	v_fma_f32 v26, -v138, v66, v26
	s_waitcnt lgkmcnt(3)
	v_fma_f32 v27, -v143, v71, v27
	v_fma_f32 v26, -v142, v70, v26
	s_waitcnt lgkmcnt(2)
	v_fma_f32 v27, -v147, v75, v27
	v_fma_f32 v26, -v146, v74, v26
	s_waitcnt lgkmcnt(1)
	v_fma_f32 v27, -v151, v79, v27
	v_fma_f32 v26, -v150, v78, v26
	v_fma_f32 v25, -v90, v25, 0
	s_waitcnt lgkmcnt(0)
	v_fma_f32 v27, -v83, v155, v27
	v_fma_f32 v26, -v154, v82, v26
	v_fma_f32 v25, -v95, v29, v25
	ds_read_b128 v[82:85], v84 offset:240
	ds_read_u16 v29, v157
	v_mul_f32_e32 v24, v89, v24
	v_fma_f32 v25, -v100, v33, v25
	v_fma_f32 v25, -v104, v37, v25
	v_fma_f32 v25, -v108, v41, v25
	s_waitcnt lgkmcnt(0)
	v_lshlrev_b32_e32 v29, 16, v29
	v_fma_f32 v24, v82, v29, -v24
	v_fma_f32 v24, -v94, v28, v24
	v_fma_f32 v24, -v99, v32, v24
	v_fma_f32 v24, -v103, v36, v24
	v_fma_f32 v24, -v107, v40, v24
	v_fma_f32 v25, -v112, v45, v25
	v_fma_f32 v24, -v111, v44, v24
	v_fma_f32 v25, -v116, v49, v25
	v_fma_f32 v24, -v115, v48, v24
	v_fma_f32 v25, -v120, v53, v25
	v_fma_f32 v24, -v119, v52, v24
	v_fma_f32 v25, -v124, v57, v25
	v_fma_f32 v24, -v123, v56, v24
	v_fma_f32 v25, -v133, v61, v25
	v_fma_f32 v24, -v127, v60, v24
	v_fma_f32 v25, -v137, v65, v25
	v_fma_f32 v24, -v136, v64, v24
	v_fma_f32 v25, -v141, v69, v25
	v_fma_f32 v24, -v140, v68, v24
	v_fma_f32 v25, -v145, v73, v25
	v_fma_f32 v24, -v144, v72, v24
	v_fma_f32 v25, -v149, v77, v25
	v_fma_f32 v24, -v148, v76, v24
	v_fma_f32 v25, -v153, v81, v25
	v_fma_f32 v24, -v152, v80, v24
	v_add_f32_e32 v24, v25, v24
	v_add_f32_e32 v25, v26, v27
	ds_read_b128 v[26:29], v92 offset:15616
	v_add_u32_e32 v156, v157, v97
	v_add_f32_e32 v24, v25, v24
	ds_read_b128 v[30:33], v92 offset:15632
	ds_read_b128 v[34:37], v92 offset:15648
	s_waitcnt lgkmcnt(2)
	v_fma_f32 v25, -v93, v29, 0
	ds_read_u16 v29, v156
	ds_read_b128 v[38:41], v92 offset:15664
	ds_read_b128 v[42:45], v92 offset:15680
	v_mul_f32_e32 v26, v89, v26
	ds_read_b128 v[46:49], v92 offset:15696
	s_waitcnt lgkmcnt(3)
	v_lshlrev_b32_e32 v29, 16, v29
	v_fma_f32 v28, -v91, v28, 0
	v_fma_f32 v27, -v90, v27, 0
	v_fma_f32 v26, v83, v29, -v26
	v_fma_f32 v25, -v98, v33, v25
	ds_read_b128 v[50:53], v92 offset:15712
	v_fma_f32 v28, -v96, v32, v28
	v_fma_f32 v27, -v95, v31, v27
	v_fma_f32 v26, -v94, v30, v26
	v_fma_f32 v25, -v102, v37, v25
	ds_read_b128 v[54:57], v92 offset:15728
	v_fma_f32 v28, -v101, v36, v28
	v_fma_f32 v27, -v100, v35, v27
	v_fma_f32 v26, -v99, v34, v26
	s_waitcnt lgkmcnt(4)
	v_fma_f32 v25, -v106, v41, v25
	ds_read_b128 v[58:61], v92 offset:15744
	v_fma_f32 v28, -v105, v40, v28
	v_fma_f32 v27, -v104, v39, v27
	v_fma_f32 v26, -v103, v38, v26
	s_waitcnt lgkmcnt(4)
	v_fma_f32 v25, -v110, v45, v25
	ds_read_b128 v[62:65], v92 offset:15760
	v_fma_f32 v28, -v109, v44, v28
	v_fma_f32 v27, -v108, v43, v27
	v_fma_f32 v26, -v107, v42, v26
	s_waitcnt lgkmcnt(4)
	v_fma_f32 v25, -v114, v49, v25
	ds_read_b128 v[66:69], v92 offset:15776
	v_fma_f32 v28, -v113, v48, v28
	v_fma_f32 v27, -v112, v47, v27
	v_fma_f32 v26, -v111, v46, v26
	s_waitcnt lgkmcnt(4)
	v_fma_f32 v25, -v118, v53, v25
	ds_read_b128 v[70:73], v92 offset:15792
	v_fma_f32 v28, -v117, v52, v28
	v_fma_f32 v27, -v116, v51, v27
	v_fma_f32 v26, -v115, v50, v26
	s_waitcnt lgkmcnt(4)
	v_fma_f32 v25, -v122, v57, v25
	ds_read_b128 v[74:77], v92 offset:15808
	v_fma_f32 v28, -v121, v56, v28
	v_fma_f32 v27, -v120, v55, v27
	v_fma_f32 v26, -v119, v54, v26
	s_waitcnt lgkmcnt(4)
	v_fma_f32 v25, -v126, v61, v25
	ds_read_b128 v[78:81], v92 offset:15824
	v_fma_f32 v28, -v125, v60, v28
	v_fma_f32 v27, -v124, v59, v27
	v_fma_f32 v26, -v123, v58, v26
	s_waitcnt lgkmcnt(4)
	v_fma_f32 v25, -v135, v65, v25
	ds_read_b128 v[158:161], v92 offset:15840
	ds_read_b128 v[162:165], v92 offset:15856
	v_fma_f32 v28, -v134, v64, v28
	v_fma_f32 v27, -v133, v63, v27
	v_fma_f32 v26, -v127, v62, v26
	s_waitcnt lgkmcnt(5)
	v_fma_f32 v25, -v139, v69, v25
	v_fma_f32 v28, -v138, v68, v28
	v_fma_f32 v27, -v137, v67, v27
	v_fma_f32 v26, -v136, v66, v26
	s_waitcnt lgkmcnt(4)
	v_fma_f32 v25, -v143, v73, v25
	v_fma_f32 v28, -v142, v72, v28
	v_fma_f32 v27, -v141, v71, v27
	v_fma_f32 v26, -v140, v70, v26
	s_waitcnt lgkmcnt(3)
	v_fma_f32 v25, -v147, v77, v25
	v_fma_f32 v28, -v146, v76, v28
	v_fma_f32 v27, -v145, v75, v27
	v_fma_f32 v26, -v144, v74, v26
	s_waitcnt lgkmcnt(2)
	v_fma_f32 v25, -v151, v81, v25
	v_fma_f32 v28, -v150, v80, v28
	v_fma_f32 v27, -v149, v79, v27
	v_fma_f32 v26, -v148, v78, v26
	s_waitcnt lgkmcnt(1)
	v_fma_f32 v25, -v155, v161, v25
	v_fma_f32 v28, -v154, v160, v28
	v_fma_f32 v27, -v153, v159, v27
	v_fma_f32 v26, -v152, v158, v26
	s_waitcnt lgkmcnt(0)
	v_fma_f32 v26, -v162, v24, v26
	v_add_f32_e32 v26, v27, v26
	v_add_f32_e32 v25, v28, v25
	v_add_f32_e32 v25, v25, v26
	ds_read_b128 v[26:29], v92 offset:15872
	ds_read_b128 v[30:33], v92 offset:15888
	v_add_u32_e32 v82, v156, v97
	ds_read_b128 v[34:37], v92 offset:15904
	ds_read_b128 v[38:41], v92 offset:15920
	s_waitcnt lgkmcnt(3)
	v_fma_f32 v27, -v90, v27, 0
	s_waitcnt lgkmcnt(2)
	v_fma_f32 v27, -v95, v31, v27
	ds_read_u16 v31, v82
	ds_read_b128 v[42:45], v92 offset:15936
	v_mul_f32_e32 v26, v89, v26
	v_fma_f32 v29, -v93, v29, 0
	ds_read_b128 v[46:49], v92 offset:15952
	s_waitcnt lgkmcnt(2)
	v_lshlrev_b32_e32 v31, 16, v31
	v_fma_f32 v28, -v91, v28, 0
	v_fma_f32 v26, v84, v31, -v26
	v_fma_f32 v29, -v98, v33, v29
	ds_read_b128 v[50:53], v92 offset:15968
	v_fma_f32 v28, -v96, v32, v28
	v_fma_f32 v26, -v94, v30, v26
	v_fma_f32 v29, -v102, v37, v29
	ds_read_b128 v[54:57], v92 offset:15984
	v_fma_f32 v28, -v101, v36, v28
	v_fma_f32 v27, -v100, v35, v27
	v_fma_f32 v26, -v99, v34, v26
	v_fma_f32 v29, -v106, v41, v29
	ds_read_b128 v[58:61], v92 offset:16000
	v_fma_f32 v28, -v105, v40, v28
	v_fma_f32 v27, -v104, v39, v27
	v_fma_f32 v26, -v103, v38, v26
	s_waitcnt lgkmcnt(4)
	v_fma_f32 v29, -v110, v45, v29
	ds_read_b128 v[62:65], v92 offset:16016
	v_fma_f32 v28, -v109, v44, v28
	v_fma_f32 v27, -v108, v43, v27
	v_fma_f32 v26, -v107, v42, v26
	s_waitcnt lgkmcnt(4)
	v_fma_f32 v29, -v114, v49, v29
	ds_read_b128 v[66:69], v92 offset:16032
	v_fma_f32 v28, -v113, v48, v28
	v_fma_f32 v27, -v112, v47, v27
	v_fma_f32 v26, -v111, v46, v26
	s_waitcnt lgkmcnt(4)
	v_fma_f32 v29, -v118, v53, v29
	ds_read_b128 v[70:73], v92 offset:16048
	v_fma_f32 v28, -v117, v52, v28
	v_fma_f32 v27, -v116, v51, v27
	v_fma_f32 v26, -v115, v50, v26
	s_waitcnt lgkmcnt(4)
	v_fma_f32 v29, -v122, v57, v29
	ds_read_b128 v[74:77], v92 offset:16064
	v_fma_f32 v28, -v121, v56, v28
	v_fma_f32 v27, -v120, v55, v27
	v_fma_f32 v26, -v119, v54, v26
	s_waitcnt lgkmcnt(4)
	v_fma_f32 v29, -v126, v61, v29
	ds_read_b128 v[78:81], v92 offset:16080
	v_fma_f32 v28, -v125, v60, v28
	v_fma_f32 v27, -v124, v59, v27
	v_fma_f32 v26, -v123, v58, v26
	s_waitcnt lgkmcnt(4)
	v_fma_f32 v29, -v135, v65, v29
	ds_read_b128 v[156:159], v92 offset:16096
	v_fma_f32 v28, -v134, v64, v28
	v_fma_f32 v27, -v133, v63, v27
	v_fma_f32 v26, -v127, v62, v26
	s_waitcnt lgkmcnt(4)
	v_fma_f32 v29, -v139, v69, v29
	ds_read_b128 v[160:163], v92 offset:16112
	v_fma_f32 v28, -v138, v68, v28
	v_fma_f32 v27, -v137, v67, v27
	v_fma_f32 v26, -v136, v66, v26
	s_waitcnt lgkmcnt(4)
	v_fma_f32 v29, -v143, v73, v29
	v_fma_f32 v28, -v142, v72, v28
	v_fma_f32 v27, -v141, v71, v27
	v_fma_f32 v26, -v140, v70, v26
	s_waitcnt lgkmcnt(3)
	v_fma_f32 v29, -v147, v77, v29
	v_fma_f32 v28, -v146, v76, v28
	v_fma_f32 v27, -v145, v75, v27
	v_fma_f32 v26, -v144, v74, v26
	s_waitcnt lgkmcnt(2)
	v_fma_f32 v29, -v151, v81, v29
	v_fma_f32 v28, -v150, v80, v28
	v_fma_f32 v27, -v149, v79, v27
	v_fma_f32 v26, -v148, v78, v26
	s_waitcnt lgkmcnt(1)
	v_fma_f32 v29, -v155, v159, v29
	v_fma_f32 v28, -v154, v158, v28
	v_fma_f32 v27, -v153, v157, v27
	v_fma_f32 v26, -v152, v156, v26
	s_waitcnt lgkmcnt(0)
	v_fma_f32 v27, -v161, v25, v27
	v_fma_f32 v26, -v24, v160, v26
	v_add_f32_e32 v26, v27, v26
	v_add_f32_e32 v27, v28, v29
	v_add_u32_e32 v83, v82, v97
	v_add_f32_e32 v82, v27, v26
	ds_read_b128 v[26:29], v92 offset:16128
	ds_read_b128 v[30:33], v92 offset:16144
	ds_read_b128 v[34:37], v92 offset:16160
	ds_read_b128 v[38:41], v92 offset:16176
	ds_read_b128 v[42:45], v92 offset:16192
	s_waitcnt lgkmcnt(4)
	v_fma_f32 v27, -v90, v27, 0
	s_waitcnt lgkmcnt(3)
	v_fma_f32 v27, -v95, v31, v27
	ds_read_u16 v31, v83
	v_mul_f32_e32 v26, v89, v26
	v_fma_f32 v29, -v93, v29, 0
	ds_read_b128 v[46:49], v92 offset:16208
	v_fma_f32 v28, -v91, v28, 0
	s_waitcnt lgkmcnt(1)
	v_lshlrev_b32_e32 v31, 16, v31
	v_fma_f32 v26, v85, v31, -v26
	v_fma_f32 v29, -v98, v33, v29
	ds_read_b128 v[50:53], v92 offset:16224
	v_fma_f32 v28, -v96, v32, v28
	v_fma_f32 v26, -v94, v30, v26
	v_fma_f32 v29, -v102, v37, v29
	ds_read_b128 v[54:57], v92 offset:16240
	v_fma_f32 v28, -v101, v36, v28
	v_fma_f32 v27, -v100, v35, v27
	v_fma_f32 v26, -v99, v34, v26
	v_fma_f32 v29, -v106, v41, v29
	ds_read_b128 v[58:61], v92 offset:16256
	v_fma_f32 v28, -v105, v40, v28
	v_fma_f32 v27, -v104, v39, v27
	v_fma_f32 v26, -v103, v38, v26
	v_fma_f32 v29, -v110, v45, v29
	ds_read_b128 v[62:65], v92 offset:16272
	v_fma_f32 v28, -v109, v44, v28
	v_fma_f32 v27, -v108, v43, v27
	v_fma_f32 v26, -v107, v42, v26
	s_waitcnt lgkmcnt(4)
	v_fma_f32 v29, -v114, v49, v29
	ds_read_b128 v[66:69], v92 offset:16288
	v_fma_f32 v28, -v113, v48, v28
	v_fma_f32 v27, -v112, v47, v27
	v_fma_f32 v26, -v111, v46, v26
	s_waitcnt lgkmcnt(4)
	v_fma_f32 v29, -v118, v53, v29
	ds_read_b128 v[70:73], v92 offset:16304
	v_fma_f32 v28, -v117, v52, v28
	v_fma_f32 v27, -v116, v51, v27
	v_fma_f32 v26, -v115, v50, v26
	s_waitcnt lgkmcnt(4)
	v_fma_f32 v29, -v122, v57, v29
	ds_read_b128 v[74:77], v92 offset:16320
	v_fma_f32 v28, -v121, v56, v28
	v_fma_f32 v27, -v120, v55, v27
	v_fma_f32 v26, -v119, v54, v26
	s_waitcnt lgkmcnt(4)
	v_fma_f32 v29, -v126, v61, v29
	ds_read_b128 v[78:81], v92 offset:16336
	v_fma_f32 v28, -v125, v60, v28
	v_fma_f32 v27, -v124, v59, v27
	v_fma_f32 v26, -v123, v58, v26
	s_waitcnt lgkmcnt(4)
	v_fma_f32 v29, -v135, v65, v29
	ds_read_b128 v[156:159], v92 offset:16352
	v_fma_f32 v28, -v134, v64, v28
	v_fma_f32 v27, -v133, v63, v27
	v_fma_f32 v26, -v127, v62, v26
	s_waitcnt lgkmcnt(4)
	v_fma_f32 v29, -v139, v69, v29
	ds_read_b128 v[160:163], v92 offset:16368
	v_fma_f32 v28, -v138, v68, v28
	v_fma_f32 v27, -v137, v67, v27
	v_fma_f32 v26, -v136, v66, v26
	s_waitcnt lgkmcnt(4)
	v_fma_f32 v29, -v143, v73, v29
	v_fma_f32 v28, -v142, v72, v28
	v_fma_f32 v27, -v141, v71, v27
	v_fma_f32 v26, -v140, v70, v26
	s_waitcnt lgkmcnt(3)
	v_fma_f32 v29, -v147, v77, v29
	v_fma_f32 v28, -v146, v76, v28
	v_fma_f32 v27, -v145, v75, v27
	v_fma_f32 v26, -v144, v74, v26
	s_waitcnt lgkmcnt(2)
	v_fma_f32 v29, -v151, v81, v29
	v_fma_f32 v28, -v150, v80, v28
	v_fma_f32 v27, -v149, v79, v27
	v_fma_f32 v26, -v148, v78, v26
	s_waitcnt lgkmcnt(1)
	v_fma_f32 v29, -v155, v159, v29
	v_fma_f32 v28, -v154, v158, v28
	v_fma_f32 v27, -v153, v157, v27
	v_fma_f32 v26, -v152, v156, v26
	s_waitcnt lgkmcnt(0)
	v_fma_f32 v28, -v162, v82, v28
	v_fma_f32 v27, -v25, v161, v27
	v_fma_f32 v26, -v24, v160, v26
	v_add_f32_e32 v26, v27, v26
	v_add_f32_e32 v27, v29, v28
	v_add_f32_e32 v30, v27, v26
	v_mov_b32_e32 v26, s53
	v_mov_b32_e32 v27, s55
	v_cndmask_b32_e64 v27, v26, v27, s[2:3]
	v_mov_b32_e32 v26, s52
	v_mov_b32_e32 v28, s54
	v_cndmask_b32_e64 v26, v26, v28, s[2:3]
	v_mov_b32_e32 v28, s7
	v_mov_b32_e32 v29, s1
	v_cndmask_b32_e32 v29, v28, v29, vcc
	v_mov_b32_e32 v28, s6
	v_mov_b32_e32 v31, s0
	v_cndmask_b32_e32 v28, v28, v31, vcc
	v_lshlrev_b64 v[28:29], 13, v[28:29]
	v_lshl_add_u64 v[26:27], v[26:27], 0, v[28:29]
	v_bfe_u32 v28, v89, 16, 1
	v_add3_u32 v28, v89, v28, s42
	v_lshl_add_u64 v[26:27], v[26:27], 0, v[128:129]
	global_store_short_d16_hi v[26:27], v28, off
	v_bfe_u32 v28, v90, 16, 1
	v_add3_u32 v28, v90, v28, s42
	global_store_short_d16_hi v[26:27], v28, off offset:128
	v_bfe_u32 v28, v91, 16, 1
	v_add3_u32 v28, v91, v28, s42
	global_store_short_d16_hi v[26:27], v28, off offset:256
	v_bfe_u32 v28, v93, 16, 1
	v_add3_u32 v28, v93, v28, s42
	global_store_short_d16_hi v[26:27], v28, off offset:384
	v_bfe_u32 v28, v94, 16, 1
	v_add3_u32 v28, v94, v28, s42
	global_store_short_d16_hi v[26:27], v28, off offset:512
	v_bfe_u32 v28, v95, 16, 1
	v_add3_u32 v28, v95, v28, s42
	global_store_short_d16_hi v[26:27], v28, off offset:640
	v_bfe_u32 v28, v96, 16, 1
	v_add3_u32 v28, v96, v28, s42
	global_store_short_d16_hi v[26:27], v28, off offset:768
	v_bfe_u32 v28, v98, 16, 1
	v_add3_u32 v28, v98, v28, s42
	global_store_short_d16_hi v[26:27], v28, off offset:896
	v_bfe_u32 v28, v99, 16, 1
	v_add3_u32 v28, v99, v28, s42
	global_store_short_d16_hi v[26:27], v28, off offset:1024
	v_bfe_u32 v28, v100, 16, 1
	v_add3_u32 v28, v100, v28, s42
	global_store_short_d16_hi v[26:27], v28, off offset:1152
	v_bfe_u32 v28, v101, 16, 1
	v_add3_u32 v28, v101, v28, s42
	global_store_short_d16_hi v[26:27], v28, off offset:1280
	v_bfe_u32 v28, v102, 16, 1
	v_add3_u32 v28, v102, v28, s42
	global_store_short_d16_hi v[26:27], v28, off offset:1408
	v_bfe_u32 v28, v103, 16, 1
	v_add3_u32 v28, v103, v28, s42
	global_store_short_d16_hi v[26:27], v28, off offset:1536
	v_bfe_u32 v28, v104, 16, 1
	v_add3_u32 v28, v104, v28, s42
	global_store_short_d16_hi v[26:27], v28, off offset:1664
	v_bfe_u32 v28, v105, 16, 1
	v_add3_u32 v28, v105, v28, s42
	global_store_short_d16_hi v[26:27], v28, off offset:1792
	v_bfe_u32 v28, v106, 16, 1
	v_add3_u32 v28, v106, v28, s42
	global_store_short_d16_hi v[26:27], v28, off offset:1920
	v_bfe_u32 v28, v107, 16, 1
	v_add3_u32 v28, v107, v28, s42
	global_store_short_d16_hi v[26:27], v28, off offset:2048
	v_bfe_u32 v28, v108, 16, 1
	v_add3_u32 v28, v108, v28, s42
	global_store_short_d16_hi v[26:27], v28, off offset:2176
	v_bfe_u32 v28, v109, 16, 1
	v_add3_u32 v28, v109, v28, s42
	global_store_short_d16_hi v[26:27], v28, off offset:2304
	v_bfe_u32 v28, v110, 16, 1
	v_add3_u32 v28, v110, v28, s42
	global_store_short_d16_hi v[26:27], v28, off offset:2432
	v_bfe_u32 v28, v111, 16, 1
	v_add3_u32 v28, v111, v28, s42
	global_store_short_d16_hi v[26:27], v28, off offset:2560
	v_bfe_u32 v28, v112, 16, 1
	v_add3_u32 v28, v112, v28, s42
	global_store_short_d16_hi v[26:27], v28, off offset:2688
	v_bfe_u32 v28, v113, 16, 1
	v_add3_u32 v28, v113, v28, s42
	global_store_short_d16_hi v[26:27], v28, off offset:2816
	v_bfe_u32 v28, v114, 16, 1
	v_add3_u32 v28, v114, v28, s42
	global_store_short_d16_hi v[26:27], v28, off offset:2944
	v_bfe_u32 v28, v115, 16, 1
	v_add3_u32 v28, v115, v28, s42
	global_store_short_d16_hi v[26:27], v28, off offset:3072
	v_bfe_u32 v28, v116, 16, 1
	v_add3_u32 v28, v116, v28, s42
	global_store_short_d16_hi v[26:27], v28, off offset:3200
	v_bfe_u32 v28, v117, 16, 1
	v_add3_u32 v28, v117, v28, s42
	global_store_short_d16_hi v[26:27], v28, off offset:3328
	v_bfe_u32 v28, v118, 16, 1
	v_add3_u32 v28, v118, v28, s42
	global_store_short_d16_hi v[26:27], v28, off offset:3456
	v_bfe_u32 v28, v119, 16, 1
	v_add3_u32 v28, v119, v28, s42
	global_store_short_d16_hi v[26:27], v28, off offset:3584
	v_bfe_u32 v28, v120, 16, 1
	v_add3_u32 v28, v120, v28, s42
	global_store_short_d16_hi v[26:27], v28, off offset:3712
	v_bfe_u32 v28, v121, 16, 1
	v_add3_u32 v28, v121, v28, s42
	global_store_short_d16_hi v[26:27], v28, off offset:3840
	v_bfe_u32 v28, v122, 16, 1
	v_add3_u32 v28, v122, v28, s42
	s_movk_i32 s0, 0x1000
	global_store_short_d16_hi v[26:27], v28, off offset:3968
	v_bfe_u32 v28, v123, 16, 1
	v_add_co_u32_e32 v26, vcc, s0, v26
	v_add3_u32 v28, v123, v28, s42
	s_nop 0
	v_addc_co_u32_e32 v27, vcc, 0, v27, vcc
	global_store_short_d16_hi v[26:27], v28, off
	v_bfe_u32 v28, v124, 16, 1
	v_add3_u32 v28, v124, v28, s42
	global_store_short_d16_hi v[26:27], v28, off offset:128
	v_bfe_u32 v28, v125, 16, 1
	v_add3_u32 v28, v125, v28, s42
	global_store_short_d16_hi v[26:27], v28, off offset:256
	v_bfe_u32 v28, v126, 16, 1
	v_add3_u32 v28, v126, v28, s42
	global_store_short_d16_hi v[26:27], v28, off offset:384
	v_bfe_u32 v28, v127, 16, 1
	v_add3_u32 v28, v127, v28, s42
	global_store_short_d16_hi v[26:27], v28, off offset:512
	v_bfe_u32 v28, v133, 16, 1
	v_add3_u32 v28, v133, v28, s42
	global_store_short_d16_hi v[26:27], v28, off offset:640
	v_bfe_u32 v28, v134, 16, 1
	v_add3_u32 v28, v134, v28, s42
	global_store_short_d16_hi v[26:27], v28, off offset:768
	v_bfe_u32 v28, v135, 16, 1
	v_add3_u32 v28, v135, v28, s42
	global_store_short_d16_hi v[26:27], v28, off offset:896
	v_bfe_u32 v28, v136, 16, 1
	v_add3_u32 v28, v136, v28, s42
	global_store_short_d16_hi v[26:27], v28, off offset:1024
	v_bfe_u32 v28, v137, 16, 1
	v_add3_u32 v28, v137, v28, s42
	global_store_short_d16_hi v[26:27], v28, off offset:1152
	v_bfe_u32 v28, v138, 16, 1
	v_add3_u32 v28, v138, v28, s42
	global_store_short_d16_hi v[26:27], v28, off offset:1280
	v_bfe_u32 v28, v139, 16, 1
	v_add3_u32 v28, v139, v28, s42
	global_store_short_d16_hi v[26:27], v28, off offset:1408
	v_bfe_u32 v28, v140, 16, 1
	v_add3_u32 v28, v140, v28, s42
	global_store_short_d16_hi v[26:27], v28, off offset:1536
	v_bfe_u32 v28, v141, 16, 1
	v_add3_u32 v28, v141, v28, s42
	global_store_short_d16_hi v[26:27], v28, off offset:1664
	v_bfe_u32 v28, v142, 16, 1
	v_add3_u32 v28, v142, v28, s42
	global_store_short_d16_hi v[26:27], v28, off offset:1792
	v_bfe_u32 v28, v143, 16, 1
	v_add3_u32 v28, v143, v28, s42
	global_store_short_d16_hi v[26:27], v28, off offset:1920
	v_bfe_u32 v28, v144, 16, 1
	v_add3_u32 v28, v144, v28, s42
	global_store_short_d16_hi v[26:27], v28, off offset:2048
	v_bfe_u32 v28, v145, 16, 1
	v_add3_u32 v28, v145, v28, s42
	global_store_short_d16_hi v[26:27], v28, off offset:2176
	v_bfe_u32 v28, v146, 16, 1
	v_add3_u32 v28, v146, v28, s42
	global_store_short_d16_hi v[26:27], v28, off offset:2304
	v_bfe_u32 v28, v147, 16, 1
	v_add3_u32 v28, v147, v28, s42
	global_store_short_d16_hi v[26:27], v28, off offset:2432
	v_bfe_u32 v28, v148, 16, 1
	v_add3_u32 v28, v148, v28, s42
	global_store_short_d16_hi v[26:27], v28, off offset:2560
	v_bfe_u32 v28, v149, 16, 1
	v_add3_u32 v28, v149, v28, s42
	global_store_short_d16_hi v[26:27], v28, off offset:2688
	v_bfe_u32 v28, v150, 16, 1
	v_add3_u32 v28, v150, v28, s42
	global_store_short_d16_hi v[26:27], v28, off offset:2816
	v_bfe_u32 v28, v151, 16, 1
	v_add3_u32 v28, v151, v28, s42
	global_store_short_d16_hi v[26:27], v28, off offset:2944
	v_bfe_u32 v28, v152, 16, 1
	v_add3_u32 v28, v152, v28, s42
	global_store_short_d16_hi v[26:27], v28, off offset:3072
	v_bfe_u32 v28, v153, 16, 1
	v_add3_u32 v28, v153, v28, s42
	global_store_short_d16_hi v[26:27], v28, off offset:3200
	v_bfe_u32 v28, v154, 16, 1
	v_add3_u32 v28, v154, v28, s42
	global_store_short_d16_hi v[26:27], v28, off offset:3328
	v_bfe_u32 v28, v155, 16, 1
	v_add3_u32 v28, v155, v28, s42
	global_store_short_d16_hi v[26:27], v28, off offset:3456
	v_bfe_u32 v28, v24, 16, 1
	v_add3_u32 v24, v24, v28, s42
	global_store_short_d16_hi v[26:27], v24, off offset:3584
	v_bfe_u32 v24, v25, 16, 1
	v_add3_u32 v24, v25, v24, s42
	global_store_short_d16_hi v[26:27], v24, off offset:3712
	v_bfe_u32 v24, v82, 16, 1
	v_add3_u32 v24, v82, v24, s42
	global_store_short_d16_hi v[26:27], v24, off offset:3840
	v_bfe_u32 v24, v30, 16, 1
	v_add3_u32 v24, v30, v24, s42
	v_readlane_b32 s0, v252, 26
	global_store_short_d16_hi v[26:27], v24, off offset:3968
	s_add_i32 s12, s0, s12
	s_cmpk_lt_i32 s12, 0x880
	s_cbranch_scc0 .LBB0_1318
